# RWKV scan LDS traffic merged: y partial stores, v reads and r reads of two tokens per instruction (ds_write2st64_b32 / ds_read2_b32 / ds_read2_b64)
# speedup vs baseline: 1.0211x; 1.0211x over previous
.LBB0_421:
	s_or_b64 exec, exec, s[18:19]
	s_mul_i32 s52, s36, 0x20800
	s_xor_b64 s[76:77], s[22:23], -1
	s_lshl_b64 s[18:19], s[52:53], 2
	s_add_u32 s18, s20, s18
	v_mov_b32_e32 v6, 0xc200
	v_mov_b32_e32 v7, 0xb000
	s_addc_u32 s19, s21, s19
	v_cndmask_b32_e64 v6, v6, v7, s[16:17]
	s_lshl_b32 s16, s34, 1
	s_add_u32 s20, s20, s16
	s_addc_u32 s21, s21, 0
	s_lshl_b32 s22, s35, 2
	s_add_u32 s18, s18, s22
	s_addc_u32 s19, s19, 0
	s_add_u32 s78, s18, 0x118000
	v_readlane_b32 s18, v255, 3
	v_lshlrev_b32_e32 v4, 1, v116
	s_addc_u32 s79, s19, 0
	v_lshl_add_u32 v61, v235, 2, s18
	s_lshl_b32 s18, s37, 1
	v_and_b32_e32 v5, 14, v4
	v_lshrrev_b32_e32 v7, 2, v116
	s_add_u32 s18, s20, s18
	v_and_b32_e32 v52, 16, v7
	s_addc_u32 s19, s21, 0
	v_lshlrev_b32_e32 v16, 1, v5
	v_ashrrev_i32_e32 v87, 4, v116
	v_add_u32_e32 v64, 0, v4
	v_lshlrev_b32_e32 v67, 5, v5
	v_lshl_add_u64 v[4:5], s[18:19], 0, v[16:17]
	v_lshlrev_b32_e32 v16, 8, v52
	v_lshl_or_b32 v69, v139, 10, v16
	v_lshl_or_b32 v16, v87, 8, v122
	v_add_u32_e32 v92, 16, v87
	v_and_b32_e32 v60, 1, v116
	v_add_u32_e32 v91, 0, v16
	v_lshl_or_b32 v16, v92, 8, v122
	v_add_u32_e32 v93, 0, v16
	v_add_u32_e32 v16, 0x11200, v64
	v_cmp_eq_u32_e32 vcc, 0, v60
	v_or_b32_e32 v7, v52, v140
	v_mul_u32_u24_e32 v7, 0x90, v7
	v_cndmask_b32_e32 v98, v61, v16, vcc
	v_add_u32_e32 v16, 0x11000, v64
	v_cndmask_b32_e32 v99, v61, v16, vcc
	v_add_u32_e32 v16, 0x10e00, v64
	v_cndmask_b32_e32 v100, v61, v16, vcc
	v_add_u32_e32 v16, 0x10c00, v64
	v_cndmask_b32_e32 v101, v61, v16, vcc
	v_add_u32_e32 v16, 0x10a00, v64
	s_mov_b64 s[18:19], 0xe488000
	v_cndmask_b32_e32 v102, v61, v16, vcc
	v_add_u32_e32 v16, 0x10800, v64
	v_add3_u32 v62, 0, v6, v7
	v_or_b32_e32 v6, s38, v140
	v_lshl_add_u64 v[18:19], v[4:5], 0, s[18:19]
	s_mov_b32 s18, 0x5040100
	s_movk_i32 s20, 0xffde
	v_add_u32_e32 v97, v106, v105
	v_cndmask_b32_e32 v103, v61, v16, vcc
	v_add_u32_e32 v16, 0x10600, v64
	v_cmp_eq_u32_e64 s[16:17], 0, v6
	v_perm_b32 v7, v153, v151, s18
	v_perm_b32 v6, v149, v147, s18
	v_perm_b32 v5, v145, v143, s18
	v_perm_b32 v4, v142, v141, s18
	v_perm_b32 v11, v165, v163, s18
	v_perm_b32 v10, v162, v161, s18
	v_perm_b32 v9, v160, v159, s18
	v_perm_b32 v8, v158, v157, s18
	v_perm_b32 v15, v186, v184, s18
	v_perm_b32 v14, v182, v180, s18
	v_perm_b32 v13, v178, v176, s18
	v_perm_b32 v12, v174, v173, s18
	v_perm_b32 v27, v198, v195, s18
	v_perm_b32 v26, v194, v193, s18
	v_perm_b32 v25, v192, v191, s18
	v_perm_b32 v24, v190, v189, s18
	v_perm_b32 v35, v156, v155, s18
	v_perm_b32 v34, v154, v152, s18
	v_perm_b32 v33, v150, v148, s18
	v_perm_b32 v32, v146, v144, s18
	v_perm_b32 v39, v172, v171, s18
	v_perm_b32 v38, v170, v169, s18
	v_perm_b32 v37, v168, v167, s18
	v_perm_b32 v36, v166, v164, s18
	v_perm_b32 v43, v188, v187, s18
	v_perm_b32 v42, v185, v183, s18
	v_perm_b32 v41, v181, v179, s18
	v_perm_b32 v40, v177, v175, s18
	v_perm_b32 v47, v204, v203, s18
	v_perm_b32 v46, v202, v201, s18
	v_perm_b32 v45, v200, v199, s18
	v_perm_b32 v44, v197, v196, s18
	v_mad_u64_u32 v[58:59], s[18:19], v97, s20, v[104:105]
	v_cndmask_b32_e32 v104, v61, v16, vcc
	v_add_u32_e32 v16, 0x10400, v64
	v_cndmask_b32_e32 v105, v61, v16, vcc
	v_add_u32_e32 v16, 0x10200, v64
	v_cndmask_b32_e32 v106, v61, v16, vcc
	v_add_u32_e32 v16, 0x10000, v64
	v_cndmask_b32_e32 v107, v61, v16, vcc
	v_add_u32_e32 v16, 0xfe00, v64
	v_cndmask_b32_e32 v108, v61, v16, vcc
	v_add_u32_e32 v16, 0xfc00, v64
	v_cndmask_b32_e32 v109, v61, v16, vcc
	v_add_u32_e32 v16, 0xfa00, v64
	v_cndmask_b32_e32 v110, v61, v16, vcc
	v_add_u32_e32 v16, 0xf800, v64
	v_cndmask_b32_e32 v111, v61, v16, vcc
	v_add_u32_e32 v16, 0xf600, v64
	v_cndmask_b32_e32 v112, v61, v16, vcc
	v_add_u32_e32 v16, 0xf400, v64
	v_cndmask_b32_e32 v113, v61, v16, vcc
	v_add_u32_e32 v16, 0xf200, v64
	v_cndmask_b32_e32 v114, v61, v16, vcc
	v_add_u32_e32 v16, 0xf000, v64
	v_add_u32_e32 v94, v206, v205
	v_cndmask_b32_e32 v115, v61, v16, vcc
	v_add_u32_e32 v16, 0xee00, v64
	v_and_b32_e32 v63, 48, v116
	v_ashrrev_i32_e32 v90, 3, v116
	v_mad_u64_u32 v[52:53], s[18:19], v94, s20, v[116:117]
	v_cndmask_b32_e32 v116, v61, v16, vcc
	v_add_u32_e32 v16, 0xec00, v64
	v_add_u32_e32 v95, v234, v233
	v_cndmask_b32_e32 v122, v61, v16, vcc
	v_add_u32_e32 v16, 0xea00, v64
	v_mad_u64_u32 v[54:55], s[18:19], v95, s20, v[124:125]
	v_add_u32_e32 v96, v237, v236
	v_cndmask_b32_e32 v124, v61, v16, vcc
	v_add_u32_e32 v16, 0xe800, v64
	v_mad_u64_u32 v[56:57], s[18:19], v96, s20, v[126:127]
	v_cndmask_b32_e32 v126, v61, v16, vcc
	v_add_u32_e32 v16, 0xe600, v64
	v_lshl_add_u32 v88, v140, 4, 0
	v_cndmask_b32_e32 v139, v61, v16, vcc
	v_add_u32_e32 v16, 0xe400, v64
	v_mad_i32_i24 v68, v140, -12, v88
	v_cndmask_b32_e32 v140, v61, v16, vcc
	v_add_u32_e32 v16, 0xe200, v64
	v_cndmask_b32_e32 v141, v61, v16, vcc
	v_add_u32_e32 v16, 0xe000, v64
	v_cndmask_b32_e32 v142, v61, v16, vcc
	v_add_u32_e32 v16, 0xde00, v64
	v_cndmask_b32_e32 v143, v61, v16, vcc
	v_add_u32_e32 v16, 0xdc00, v64
	v_cndmask_b32_e32 v144, v61, v16, vcc
	v_add_u32_e32 v16, 0xda00, v64
	v_cndmask_b32_e32 v145, v61, v16, vcc
	v_add_u32_e32 v16, 0xd800, v64
	v_cndmask_b32_e32 v146, v61, v16, vcc
	v_add_u32_e32 v16, 0xd600, v64
	v_cndmask_b32_e32 v147, v61, v16, vcc
	v_and_b32_e32 v16, -16, v52
	v_add_u32_e32 v65, 0xd400, v64
	v_cmp_ne_u32_e64 s[18:19], 16, v16
	v_lshl_add_u32 v16, v94, 6, 0
	v_lshlrev_b32_e32 v53, 5, v52
	s_mov_b32 s28, 0x9c00
	s_movk_i32 s29, 0xc0
	s_movk_i32 s30, 0xff90
	v_cndmask_b32_e32 v148, v61, v65, vcc
	v_add3_u32 v55, v16, v53, s28
	v_mad_u64_u32 v[60:61], s[20:21], v94, s29, v[16:17]
	v_mul_lo_u32 v16, v94, s30
	v_lshlrev_b32_e32 v59, 4, v52
	v_add3_u32 v59, v60, v16, v59
	v_and_b32_e32 v16, -16, v54
	v_cmp_ne_u32_e64 s[20:21], 16, v16
	v_lshl_add_u32 v16, v95, 6, 0
	v_add_u32_e32 v53, v60, v53
	v_lshlrev_b32_e32 v64, 5, v54
	v_mad_u64_u32 v[60:61], s[22:23], v95, s29, v[16:17]
	v_add3_u32 v65, v16, v64, s28
	v_mul_lo_u32 v16, v95, s30
	v_lshlrev_b32_e32 v61, 4, v54
	v_add3_u32 v71, v60, v16, v61
	v_and_b32_e32 v16, -16, v56
	v_cmp_ne_u32_e64 s[22:23], 16, v16
	v_lshl_add_u32 v16, v96, 6, 0
	v_add_u32_e32 v64, v60, v64
	v_lshlrev_b32_e32 v72, 5, v56
	v_mad_u64_u32 v[60:61], s[24:25], v96, s29, v[16:17]
	v_add3_u32 v82, v16, v72, s28
	v_mul_lo_u32 v16, v96, s30
	v_lshlrev_b32_e32 v61, 4, v56
	v_add3_u32 v158, v60, v16, v61
	v_and_b32_e32 v16, -16, v58
	v_cmp_ne_u32_e64 s[24:25], 16, v16
	v_lshl_add_u32 v16, v97, 6, 0
	v_add_u32_e32 v83, v60, v72
	v_lshlrev_b32_e32 v72, 5, v58
	v_mad_u64_u32 v[60:61], s[26:27], v97, s29, v[16:17]
	v_add3_u32 v152, v16, v72, s28
	v_mul_lo_u32 v16, v97, s30
	v_lshlrev_b32_e32 v61, 4, v58
	v_add3_u32 v159, v60, v16, v61
	v_lshl_add_u32 v16, v86, 6, 0
	v_add_u32_e32 v153, v60, v72
	v_lshlrev_b32_e32 v72, 5, v84
	v_mad_u64_u32 v[60:61], s[26:27], v86, s29, v[16:17]
	v_add3_u32 v155, v16, v72, s28
	v_add_u32_e32 v16, v60, v72
	v_mul_lo_u32 v61, v86, s30
	v_lshlrev_b32_e32 v72, 4, v84
	v_mov_b32_e32 v149, s40
	v_mov_b32_e32 v150, s41
	v_cmp_gt_u32_e64 s[26:27], 32, v52
	v_add3_u32 v160, v60, v61, v72
	v_mov_b32_e32 v80, s42
	v_mov_b32_e32 v81, s34
	v_cmp_gt_i32_e32 vcc, 8, v52
	v_cndmask_b32_e64 v61, v149, v150, s[26:27]
	v_mov_b32_e32 v151, s39
	v_cmp_gt_u32_e64 s[26:27], 24, v52
	v_cndmask_b32_e32 v60, v80, v81, vcc
	v_cmp_gt_i32_e64 s[28:29], 16, v52
	v_cndmask_b32_e64 v61, v61, v151, s[26:27]
	v_cmp_gt_u32_e64 s[30:31], 32, v54
	v_cndmask_b32_e64 v60, v61, v60, s[28:29]
	v_lshl_add_u32 v60, v52, 3, v60
	v_ashrrev_i32_e32 v61, 31, v60
	v_lshl_add_u64 v[72:73], v[60:61], 1, s[58:59]
	v_cmp_gt_i32_e64 s[28:29], 8, v54
	v_cndmask_b32_e64 v61, v149, v150, s[30:31]
	v_cmp_gt_u32_e64 s[30:31], 24, v54
	v_cndmask_b32_e64 v60, v80, v81, s[28:29]
	v_cmp_gt_i32_e64 s[34:35], 16, v54
	v_cndmask_b32_e64 v61, v61, v151, s[30:31]
	v_cmp_gt_u32_e64 s[36:37], 32, v56
	v_cndmask_b32_e64 v60, v61, v60, s[34:35]
	v_lshl_add_u32 v60, v54, 3, v60
	v_ashrrev_i32_e32 v61, 31, v60
	v_lshl_add_u64 v[74:75], v[60:61], 1, s[58:59]
	v_cmp_gt_i32_e64 s[34:35], 8, v56
	v_cndmask_b32_e64 v61, v149, v150, s[36:37]
	v_cmp_gt_u32_e64 s[36:37], 24, v56
	v_cndmask_b32_e64 v60, v80, v81, s[34:35]
	v_cmp_gt_i32_e64 s[38:39], 16, v56
	v_cndmask_b32_e64 v61, v61, v151, s[36:37]
	v_cmp_gt_u32_e64 s[40:41], 32, v58
	v_cndmask_b32_e64 v60, v61, v60, s[38:39]
	v_lshl_add_u32 v60, v56, 3, v60
	v_ashrrev_i32_e32 v61, 31, v60
	v_lshl_add_u64 v[76:77], v[60:61], 1, s[58:59]
	v_cmp_gt_i32_e64 s[38:39], 8, v58
	v_cndmask_b32_e64 v61, v149, v150, s[40:41]
	v_cmp_gt_u32_e64 s[40:41], 24, v58
	v_cndmask_b32_e64 v60, v80, v81, s[38:39]
	v_cmp_gt_i32_e64 s[42:43], 16, v58
	v_cndmask_b32_e64 v61, v61, v151, s[40:41]
	v_cmp_gt_u32_e64 s[44:45], 32, v84
	v_cndmask_b32_e64 v60, v61, v60, s[42:43]
	v_lshl_add_u32 v60, v58, 3, v60
	v_ashrrev_i32_e32 v61, 31, v60
	v_lshl_add_u64 v[78:79], v[60:61], 1, s[58:59]
	v_cmp_gt_i32_e64 s[42:43], 8, v84
	v_cndmask_b32_e64 v61, v149, v150, s[44:45]
	v_cmp_gt_u32_e64 s[44:45], 24, v84
	v_cndmask_b32_e64 v60, v80, v81, s[42:43]
	v_cmp_gt_i32_e64 s[48:49], 16, v84
	v_cndmask_b32_e64 v61, v61, v151, s[44:45]
	v_add_u32_e32 v57, 0x1f00, v53
	v_cndmask_b32_e64 v60, v61, v60, s[48:49]
	v_cmp_gt_u32_e64 s[48:49], 16, v52
	v_add_u32_e32 v70, 0x1f00, v64
	v_add_u32_e32 v85, 0x1f00, v83
	v_cndmask_b32_e64 v52, v55, v57, s[48:49]
	v_cndmask_b32_e32 v149, v52, v53, vcc
	v_cmp_gt_u32_e32 vcc, 16, v54
	v_add_u32_e32 v154, 0x1f00, v153
	v_add_u32_e32 v156, 0x1f00, v16
	v_cndmask_b32_e32 v53, v65, v70, vcc
	v_cmp_gt_u32_e32 vcc, 16, v56
	v_lshl_add_u32 v60, v84, 3, v60
	v_mov_b32_e32 v57, 0xc080
	v_cndmask_b32_e32 v54, v82, v85, vcc
	v_cmp_gt_u32_e32 vcc, 16, v58
	v_lshl_add_u32 v66, v90, 9, 0
	v_ashrrev_i32_e32 v61, 31, v60
	v_cndmask_b32_e32 v55, v152, v154, vcc
	v_cmp_gt_u32_e32 vcc, 16, v84
	v_cndmask_b32_e64 v52, v57, v254, s[26:27]
	v_cndmask_b32_e64 v150, v53, v64, s[28:29]
	v_cndmask_b32_e32 v56, v155, v156, vcc
	v_cndmask_b32_e64 v53, v57, v254, s[30:31]
	v_cndmask_b32_e64 v151, v54, v83, s[34:35]
	v_cndmask_b32_e64 v54, v57, v254, s[36:37]
	v_cndmask_b32_e64 v152, v55, v153, s[38:39]
	v_cndmask_b32_e64 v55, v57, v254, s[40:41]
	v_cndmask_b32_e64 v153, v56, v16, s[42:43]
	v_cndmask_b32_e64 v56, v57, v254, s[44:45]
	v_mov_b32_e32 v16, v17
	v_lshl_add_u32 v89, v87, 2, 0
	v_lshl_add_u64 v[80:81], v[60:61], 1, s[58:59]
	s_mov_b32 s34, -8
	v_add_u32_e32 v154, v62, v63
	v_add_u32_e32 v155, v66, v67
	v_add_u32_e32 v156, v59, v52
	v_add_u32_e32 v157, v71, v53
	v_add_u32_e32 v158, v158, v54
	v_add_u32_e32 v159, v159, v55
	v_add_u32_e32 v160, v160, v56
	v_add_u32_e32 v161, v68, v69
	v_mov_b64_e32 v[82:83], v[16:17]
	v_mov_b64_e32 v[84:85], v[16:17]
	v_mov_b32_e32 v52, v232
	v_mov_b32_e32 v53, v231
	v_mov_b32_e32 v54, v230
	v_mov_b32_e32 v55, v207
	s_waitcnt lgkmcnt(0)
	s_barrier
	v_mad_u64_u32 v[218:219], s[26:27], v94, s83, v[72:73]
	v_mad_u64_u32 v[220:221], s[26:27], v95, s83, v[74:75]
	v_mad_u64_u32 v[222:223], s[26:27], v96, s83, v[76:77]
	v_mad_u64_u32 v[244:245], s[26:27], v97, s83, v[78:79]
	v_mad_u64_u32 v[246:247], s[26:27], v86, s83, v[80:81]
	v_and_b32_e32 v98, 31, v119
	v_lshlrev_b32_e32 v98, 3, v98
	v_lshrrev_b32_e32 v99, 5, v119
	s_lshl_b32 s26, s32, 3
	v_add_u32_e32 v99, s26, v99
	v_lshl_add_u32 v99, v99, 2, v228
	v_add_u32_e32 v99, 0x6000, v99
	v_lshrrev_b32_e32 v100, 1, v119
	v_lshlrev_b32_e32 v100, 2, v100
	v_add_u32_e32 v100, 0xd400, v100
	v_lshrrev_b32_e32 v101, 3, v119
	v_lshlrev_b32_e32 v101, 9, v101
	v_and_b32_e32 v102, 7, v119
	v_lshl_add_u32 v101, v102, 6, v101
	v_add_u32_e32 v101, 0xd400, v101
	v_sub_u32_e32 v102, s26, v102
	v_lshlrev_b32_e32 v102, 1, v102
	v_ashrrev_i32_e32 v103, 31, v102
	v_lshl_add_u64 v[102:103], v[18:19], 0, v[102:103]
	s_load_dwordx2 s[26:27], s[84:85], 0x120
	v_lshrrev_b32_e32 v60, 3, v119
	v_and_b32_e32 v61, 7, v119
	v_mov_b32_e32 v62, s82
	v_add_u32_e32 v62, 0xffffff80, v62
	v_bfe_u32 v63, v62, 2, 3
	v_lshlrev_b32_e32 v63, 6, v63
	v_lshrrev_b32_e32 v64, 5, v62
	v_lshlrev_b32_e32 v64, 6, v64
	v_and_b32_e32 v65, 3, v62
	v_lshlrev_b32_e32 v65, 4, v65
	v_lshl_add_u32 v66, v61, 3, v63
	v_lshl_add_u32 v67, v61, 3, v64
	v_add_u32_e32 v67, 0x600, v67
	v_and_b32_e32 v68, 1, v119
	v_lshl_add_u32 v69, v68, 3, v63
	v_add_u32_e32 v69, v69, v65
	v_add_u32_e32 v69, 0x400, v69
	v_mul_u32_u24_e32 v70, 0x1200, v60
	v_lshrrev_b32_e32 v71, 1, v119
	v_mul_u32_u24_e32 v162, 0x1200, v71
	s_waitcnt lgkmcnt(0)
	s_add_u32 s26, s26, 0x6aa8000
	s_addc_u32 s27, s27, 0
	v_lshl_add_u32 v16, v66, 1, v70
	v_lshl_add_u64 v[218:219], v[16:17], 0, s[26:27]
	v_add_u32_e32 v16, 0x400, v16
	v_lshl_add_u64 v[220:221], v[16:17], 0, s[26:27]
	v_lshl_add_u32 v16, v67, 1, v70
	v_lshl_add_u64 v[222:223], v[16:17], 0, s[26:27]
	v_add_u32_e32 v16, 0x100, v16
	v_lshl_add_u64 v[244:245], v[16:17], 0, s[26:27]
	v_lshl_add_u32 v16, v69, 1, v162
	v_lshl_add_u64 v[246:247], v[16:17], 0, s[26:27]
	v_lshlrev_b32_e32 v149, 8, v60
	v_lshl_add_u32 v149, v61, 5, v149
	v_add_u32_e32 v150, 0x2000, v149
	v_mul_u32_u24_e32 v156, 0x90, v60
	v_lshl_add_u32 v156, v61, 4, v156
	v_add_u32_e32 v156, 0xb000, v156
	v_add_u32_e32 v157, 0x1200, v156
	v_lshlrev_b32_e32 v151, 6, v71
	v_lshl_add_u32 v151, v68, 5, v151
	v_add_u32_e32 v151, 0xa000, v151
	v_mul_f32_e32 v117, s73, v117
	v_mul_f32_e32 v121, s73, v121
	v_mul_f32_e32 v123, s73, v123
	v_mul_f32_e32 v125, s73, v125
	v_add_u32_e32 v153, 0x100, v98
	v_add_u32_e32 v159, 0x400, v99
	v_add_u32_e32 v160, 0x800, v98
	v_add_u32_e32 v230, 0x1000, v98
	v_add_u32_e32 v231, 0x1800, v98
	v_add_u32_e32 v152, 0x8000, v161
	v_add_u32_e32 v158, 0x4000, v161
	s_branch .LBB0_424

.LBB0_514:
	s_andn2_b64 vcc, exec, s[62:63]
	s_cbranch_vccnz .Lrs_fwd
	ds_read2st64_b64 v[162:165], v153 offset0:63 offset1:47
	ds_read2st64_b64 v[166:169], v153 offset0:31 offset1:79
	ds_read2_b32 v[200:201], v159 offset0:240 offset1:224
	ds_read2st64_b64 v[174:177], v98 offset0:63 offset1:47
	ds_read2st64_b64 v[178:181], v98 offset0:31 offset1:79
	ds_read2_b64 v[186:189], v231 offset0:224 offset1:192
	s_waitcnt lgkmcnt(3)
	v_pk_mul_f32 v[190:191], v[82:83], v[162:163]
	v_add_f32_e32 v196, v190, v191
	v_pk_mul_f32 v[194:195], v[82:83], v[164:165]
	s_nop 0
	v_add_f32_dpp v196, v196, v196 quad_perm:[1,0,3,2] row_mask:0xf bank_mask:0xf bound_ctrl:1
	v_pk_fma_f32 v[194:195], v[200:201], v[166:167], v[194:195] op_sel_hi:[0,1,1]
	s_nop 0
	v_add_f32_dpp v196, v196, v196 quad_perm:[2,3,0,1] row_mask:0xf bank_mask:0xf bound_ctrl:1
	s_nop 1
	v_add_f32_dpp v196, v196, v196 row_half_mirror row_mask:0xf bank_mask:0xf bound_ctrl:1
	s_nop 1
	v_add_f32_dpp v196, v196, v196 row_mirror row_mask:0xf bank_mask:0xf bound_ctrl:1
	v_mov_b32_e32 v197, v196
	s_nop 1
	v_permlane16_swap_b32_e32 v196, v197
	v_add_f32_e32 v196, v196, v197
	v_pk_fma_f32 v[82:83], v[196:197], v[168:169], v[194:195] op_sel_hi:[0,1,1] neg_lo:[1,0,0] neg_hi:[1,0,0]
	ds_read2st64_b64 v[162:165], v153 offset0:62 offset1:46
	ds_read2st64_b64 v[166:169], v153 offset0:30 offset1:78
	ds_read2_b32 v[202:203], v159 offset0:208 offset1:192
	s_waitcnt lgkmcnt(3)
	v_pk_mul_f32 v[190:191], v[82:83], v[174:175]
	v_add_f32_e32 v196, v190, v191
	v_pk_mul_f32 v[192:193], v[82:83], v[186:187]
	v_pk_mul_f32 v[194:195], v[82:83], v[176:177]
	v_add_f32_dpp v196, v196, v196 quad_perm:[1,0,3,2] row_mask:0xf bank_mask:0xf bound_ctrl:1
	v_add_f32_e32 v198, v192, v193
	v_pk_fma_f32 v[194:195], v[200:201], v[178:179], v[194:195] op_sel:[1,0,0] op_sel_hi:[1,1,1]
	v_add_f32_dpp v196, v196, v196 quad_perm:[2,3,0,1] row_mask:0xf bank_mask:0xf bound_ctrl:1
	v_add_f32_dpp v198, v198, v198 quad_perm:[1,0,3,2] row_mask:0xf bank_mask:0xf bound_ctrl:1
	s_nop 0
	v_add_f32_dpp v196, v196, v196 row_half_mirror row_mask:0xf bank_mask:0xf bound_ctrl:1
	s_nop 1
	v_add_f32_dpp v196, v196, v196 row_mirror row_mask:0xf bank_mask:0xf bound_ctrl:1
	v_mov_b32_e32 v197, v196
	s_nop 1
	v_permlane16_swap_b32_e32 v196, v197
	v_add_f32_e32 v196, v196, v197
	v_pk_fma_f32 v[82:83], v[196:197], v[180:181], v[194:195] op_sel_hi:[0,1,1] neg_lo:[1,0,0] neg_hi:[1,0,0]
	ds_read2st64_b64 v[174:177], v98 offset0:62 offset1:46
	ds_read2st64_b64 v[178:181], v98 offset0:30 offset1:78
	ds_read2_b64 v[204:207], v231 offset0:160 offset1:128
	s_waitcnt lgkmcnt(3)
	v_pk_mul_f32 v[190:191], v[82:83], v[162:163]
	v_add_f32_e32 v196, v190, v191
	v_pk_mul_f32 v[192:193], v[82:83], v[188:189]
	v_pk_mul_f32 v[194:195], v[82:83], v[164:165]
	v_add_f32_dpp v196, v196, v196 quad_perm:[1,0,3,2] row_mask:0xf bank_mask:0xf bound_ctrl:1
	v_add_f32_e32 v199, v192, v193
	v_pk_fma_f32 v[194:195], v[202:203], v[166:167], v[194:195] op_sel_hi:[0,1,1]
	v_add_f32_dpp v196, v196, v196 quad_perm:[2,3,0,1] row_mask:0xf bank_mask:0xf bound_ctrl:1
	v_add_f32_dpp v199, v199, v199 quad_perm:[1,0,3,2] row_mask:0xf bank_mask:0xf bound_ctrl:1
	ds_write2st64_b32 v100, v198, v199 offset0:62 offset1:60
	v_add_f32_dpp v196, v196, v196 row_half_mirror row_mask:0xf bank_mask:0xf bound_ctrl:1
	s_nop 1
	v_add_f32_dpp v196, v196, v196 row_mirror row_mask:0xf bank_mask:0xf bound_ctrl:1
	v_mov_b32_e32 v197, v196
	s_nop 1
	v_permlane16_swap_b32_e32 v196, v197
	v_add_f32_e32 v196, v196, v197
	v_pk_fma_f32 v[82:83], v[196:197], v[168:169], v[194:195] op_sel_hi:[0,1,1] neg_lo:[1,0,0] neg_hi:[1,0,0]
	ds_read2st64_b64 v[162:165], v153 offset0:61 offset1:45
	ds_read2st64_b64 v[166:169], v153 offset0:29 offset1:77
	ds_read2_b32 v[200:201], v159 offset0:176 offset1:160
	s_waitcnt lgkmcnt(4)
	v_pk_mul_f32 v[190:191], v[82:83], v[174:175]
	v_add_f32_e32 v196, v190, v191
	v_pk_mul_f32 v[192:193], v[82:83], v[204:205]
	v_pk_mul_f32 v[194:195], v[82:83], v[176:177]
	v_add_f32_dpp v196, v196, v196 quad_perm:[1,0,3,2] row_mask:0xf bank_mask:0xf bound_ctrl:1
	v_add_f32_e32 v198, v192, v193
	v_pk_fma_f32 v[194:195], v[202:203], v[178:179], v[194:195] op_sel:[1,0,0] op_sel_hi:[1,1,1]
	v_add_f32_dpp v196, v196, v196 quad_perm:[2,3,0,1] row_mask:0xf bank_mask:0xf bound_ctrl:1
	v_add_f32_dpp v198, v198, v198 quad_perm:[1,0,3,2] row_mask:0xf bank_mask:0xf bound_ctrl:1
	s_nop 0
	v_add_f32_dpp v196, v196, v196 row_half_mirror row_mask:0xf bank_mask:0xf bound_ctrl:1
	s_nop 1
	v_add_f32_dpp v196, v196, v196 row_mirror row_mask:0xf bank_mask:0xf bound_ctrl:1
	v_mov_b32_e32 v197, v196
	s_nop 1
	v_permlane16_swap_b32_e32 v196, v197
	v_add_f32_e32 v196, v196, v197
	v_pk_fma_f32 v[82:83], v[196:197], v[180:181], v[194:195] op_sel_hi:[0,1,1] neg_lo:[1,0,0] neg_hi:[1,0,0]
	ds_read2st64_b64 v[174:177], v98 offset0:61 offset1:45
	ds_read2st64_b64 v[178:181], v98 offset0:29 offset1:77
	ds_read2_b64 v[186:189], v231 offset0:96 offset1:64
	s_waitcnt lgkmcnt(3)
	v_pk_mul_f32 v[190:191], v[82:83], v[162:163]
	v_add_f32_e32 v196, v190, v191
	v_pk_mul_f32 v[192:193], v[82:83], v[206:207]
	v_pk_mul_f32 v[194:195], v[82:83], v[164:165]
	v_add_f32_dpp v196, v196, v196 quad_perm:[1,0,3,2] row_mask:0xf bank_mask:0xf bound_ctrl:1
	v_add_f32_e32 v199, v192, v193
	v_pk_fma_f32 v[194:195], v[200:201], v[166:167], v[194:195] op_sel_hi:[0,1,1]
	v_add_f32_dpp v196, v196, v196 quad_perm:[2,3,0,1] row_mask:0xf bank_mask:0xf bound_ctrl:1
	v_add_f32_dpp v199, v199, v199 quad_perm:[1,0,3,2] row_mask:0xf bank_mask:0xf bound_ctrl:1
	ds_write2st64_b32 v100, v198, v199 offset0:58 offset1:56
	v_add_f32_dpp v196, v196, v196 row_half_mirror row_mask:0xf bank_mask:0xf bound_ctrl:1
	s_nop 1
	v_add_f32_dpp v196, v196, v196 row_mirror row_mask:0xf bank_mask:0xf bound_ctrl:1
	v_mov_b32_e32 v197, v196
	s_nop 1
	v_permlane16_swap_b32_e32 v196, v197
	v_add_f32_e32 v196, v196, v197
	v_pk_fma_f32 v[82:83], v[196:197], v[168:169], v[194:195] op_sel_hi:[0,1,1] neg_lo:[1,0,0] neg_hi:[1,0,0]
	ds_read2st64_b64 v[162:165], v153 offset0:60 offset1:44
	ds_read2st64_b64 v[166:169], v153 offset0:28 offset1:76
	ds_read2_b32 v[202:203], v159 offset0:144 offset1:128
	s_waitcnt lgkmcnt(4)
	v_pk_mul_f32 v[190:191], v[82:83], v[174:175]
	v_add_f32_e32 v196, v190, v191
	v_pk_mul_f32 v[192:193], v[82:83], v[186:187]
	v_pk_mul_f32 v[194:195], v[82:83], v[176:177]
	v_add_f32_dpp v196, v196, v196 quad_perm:[1,0,3,2] row_mask:0xf bank_mask:0xf bound_ctrl:1
	v_add_f32_e32 v198, v192, v193
	v_pk_fma_f32 v[194:195], v[200:201], v[178:179], v[194:195] op_sel:[1,0,0] op_sel_hi:[1,1,1]
	v_add_f32_dpp v196, v196, v196 quad_perm:[2,3,0,1] row_mask:0xf bank_mask:0xf bound_ctrl:1
	v_add_f32_dpp v198, v198, v198 quad_perm:[1,0,3,2] row_mask:0xf bank_mask:0xf bound_ctrl:1
	s_nop 0
	v_add_f32_dpp v196, v196, v196 row_half_mirror row_mask:0xf bank_mask:0xf bound_ctrl:1
	s_nop 1
	v_add_f32_dpp v196, v196, v196 row_mirror row_mask:0xf bank_mask:0xf bound_ctrl:1
	v_mov_b32_e32 v197, v196
	s_nop 1
	v_permlane16_swap_b32_e32 v196, v197
	v_add_f32_e32 v196, v196, v197
	v_pk_fma_f32 v[82:83], v[196:197], v[180:181], v[194:195] op_sel_hi:[0,1,1] neg_lo:[1,0,0] neg_hi:[1,0,0]
	ds_read2st64_b64 v[174:177], v98 offset0:60 offset1:44
	ds_read2st64_b64 v[178:181], v98 offset0:28 offset1:76
	ds_read2_b64 v[204:207], v231 offset0:32 offset1:0
	s_waitcnt lgkmcnt(3)
	v_pk_mul_f32 v[190:191], v[82:83], v[162:163]
	v_add_f32_e32 v196, v190, v191
	v_pk_mul_f32 v[192:193], v[82:83], v[188:189]
	v_pk_mul_f32 v[194:195], v[82:83], v[164:165]
	v_add_f32_dpp v196, v196, v196 quad_perm:[1,0,3,2] row_mask:0xf bank_mask:0xf bound_ctrl:1
	v_add_f32_e32 v199, v192, v193
	v_pk_fma_f32 v[194:195], v[202:203], v[166:167], v[194:195] op_sel_hi:[0,1,1]
	v_add_f32_dpp v196, v196, v196 quad_perm:[2,3,0,1] row_mask:0xf bank_mask:0xf bound_ctrl:1
	v_add_f32_dpp v199, v199, v199 quad_perm:[1,0,3,2] row_mask:0xf bank_mask:0xf bound_ctrl:1
	ds_write2st64_b32 v100, v198, v199 offset0:54 offset1:52
	v_add_f32_dpp v196, v196, v196 row_half_mirror row_mask:0xf bank_mask:0xf bound_ctrl:1
	s_nop 1
	v_add_f32_dpp v196, v196, v196 row_mirror row_mask:0xf bank_mask:0xf bound_ctrl:1
	v_mov_b32_e32 v197, v196
	s_nop 1
	v_permlane16_swap_b32_e32 v196, v197
	v_add_f32_e32 v196, v196, v197
	v_pk_fma_f32 v[82:83], v[196:197], v[168:169], v[194:195] op_sel_hi:[0,1,1] neg_lo:[1,0,0] neg_hi:[1,0,0]
	ds_read2st64_b64 v[162:165], v153 offset0:59 offset1:43
	ds_read2st64_b64 v[166:169], v153 offset0:27 offset1:75
	ds_read2_b32 v[200:201], v159 offset0:112 offset1:96
	s_waitcnt lgkmcnt(4)
	v_pk_mul_f32 v[190:191], v[82:83], v[174:175]
	v_add_f32_e32 v196, v190, v191
	v_pk_mul_f32 v[192:193], v[82:83], v[204:205]
	v_pk_mul_f32 v[194:195], v[82:83], v[176:177]
	v_add_f32_dpp v196, v196, v196 quad_perm:[1,0,3,2] row_mask:0xf bank_mask:0xf bound_ctrl:1
	v_add_f32_e32 v198, v192, v193
	v_pk_fma_f32 v[194:195], v[202:203], v[178:179], v[194:195] op_sel:[1,0,0] op_sel_hi:[1,1,1]
	v_add_f32_dpp v196, v196, v196 quad_perm:[2,3,0,1] row_mask:0xf bank_mask:0xf bound_ctrl:1
	v_add_f32_dpp v198, v198, v198 quad_perm:[1,0,3,2] row_mask:0xf bank_mask:0xf bound_ctrl:1
	s_nop 0
	v_add_f32_dpp v196, v196, v196 row_half_mirror row_mask:0xf bank_mask:0xf bound_ctrl:1
	s_nop 1
	v_add_f32_dpp v196, v196, v196 row_mirror row_mask:0xf bank_mask:0xf bound_ctrl:1
	v_mov_b32_e32 v197, v196
	s_nop 1
	v_permlane16_swap_b32_e32 v196, v197
	v_add_f32_e32 v196, v196, v197
	v_pk_fma_f32 v[82:83], v[196:197], v[180:181], v[194:195] op_sel_hi:[0,1,1] neg_lo:[1,0,0] neg_hi:[1,0,0]
	ds_read2st64_b64 v[174:177], v98 offset0:59 offset1:43
	ds_read2st64_b64 v[178:181], v98 offset0:27 offset1:75
	ds_read2_b64 v[186:189], v230 offset0:224 offset1:192
	s_waitcnt lgkmcnt(3)
	v_pk_mul_f32 v[190:191], v[82:83], v[162:163]
	v_add_f32_e32 v196, v190, v191
	v_pk_mul_f32 v[192:193], v[82:83], v[206:207]
	v_pk_mul_f32 v[194:195], v[82:83], v[164:165]
	v_add_f32_dpp v196, v196, v196 quad_perm:[1,0,3,2] row_mask:0xf bank_mask:0xf bound_ctrl:1
	v_add_f32_e32 v199, v192, v193
	v_pk_fma_f32 v[194:195], v[200:201], v[166:167], v[194:195] op_sel_hi:[0,1,1]
	v_add_f32_dpp v196, v196, v196 quad_perm:[2,3,0,1] row_mask:0xf bank_mask:0xf bound_ctrl:1
	v_add_f32_dpp v199, v199, v199 quad_perm:[1,0,3,2] row_mask:0xf bank_mask:0xf bound_ctrl:1
	ds_write2st64_b32 v100, v198, v199 offset0:50 offset1:48
	v_add_f32_dpp v196, v196, v196 row_half_mirror row_mask:0xf bank_mask:0xf bound_ctrl:1
	s_nop 1
	v_add_f32_dpp v196, v196, v196 row_mirror row_mask:0xf bank_mask:0xf bound_ctrl:1
	v_mov_b32_e32 v197, v196
	s_nop 1
	v_permlane16_swap_b32_e32 v196, v197
	v_add_f32_e32 v196, v196, v197
	v_pk_fma_f32 v[82:83], v[196:197], v[168:169], v[194:195] op_sel_hi:[0,1,1] neg_lo:[1,0,0] neg_hi:[1,0,0]
	ds_read2st64_b64 v[162:165], v153 offset0:58 offset1:42
	ds_read2st64_b64 v[166:169], v153 offset0:26 offset1:74
	ds_read2_b32 v[202:203], v159 offset0:80 offset1:64
	s_waitcnt lgkmcnt(4)
	v_pk_mul_f32 v[190:191], v[82:83], v[174:175]
	v_add_f32_e32 v196, v190, v191
	v_pk_mul_f32 v[192:193], v[82:83], v[186:187]
	v_pk_mul_f32 v[194:195], v[82:83], v[176:177]
	v_add_f32_dpp v196, v196, v196 quad_perm:[1,0,3,2] row_mask:0xf bank_mask:0xf bound_ctrl:1
	v_add_f32_e32 v198, v192, v193
	v_pk_fma_f32 v[194:195], v[200:201], v[178:179], v[194:195] op_sel:[1,0,0] op_sel_hi:[1,1,1]
	v_add_f32_dpp v196, v196, v196 quad_perm:[2,3,0,1] row_mask:0xf bank_mask:0xf bound_ctrl:1
	v_add_f32_dpp v198, v198, v198 quad_perm:[1,0,3,2] row_mask:0xf bank_mask:0xf bound_ctrl:1
	s_nop 0
	v_add_f32_dpp v196, v196, v196 row_half_mirror row_mask:0xf bank_mask:0xf bound_ctrl:1
	s_nop 1
	v_add_f32_dpp v196, v196, v196 row_mirror row_mask:0xf bank_mask:0xf bound_ctrl:1
	v_mov_b32_e32 v197, v196
	s_nop 1
	v_permlane16_swap_b32_e32 v196, v197
	v_add_f32_e32 v196, v196, v197
	v_pk_fma_f32 v[82:83], v[196:197], v[180:181], v[194:195] op_sel_hi:[0,1,1] neg_lo:[1,0,0] neg_hi:[1,0,0]
	ds_read2st64_b64 v[174:177], v98 offset0:58 offset1:42
	ds_read2st64_b64 v[178:181], v98 offset0:26 offset1:74
	ds_read2_b64 v[204:207], v230 offset0:160 offset1:128
	s_waitcnt lgkmcnt(3)
	v_pk_mul_f32 v[190:191], v[82:83], v[162:163]
	v_add_f32_e32 v196, v190, v191
	v_pk_mul_f32 v[192:193], v[82:83], v[188:189]
	v_pk_mul_f32 v[194:195], v[82:83], v[164:165]
	v_add_f32_dpp v196, v196, v196 quad_perm:[1,0,3,2] row_mask:0xf bank_mask:0xf bound_ctrl:1
	v_add_f32_e32 v199, v192, v193
	v_pk_fma_f32 v[194:195], v[202:203], v[166:167], v[194:195] op_sel_hi:[0,1,1]
	v_add_f32_dpp v196, v196, v196 quad_perm:[2,3,0,1] row_mask:0xf bank_mask:0xf bound_ctrl:1
	v_add_f32_dpp v199, v199, v199 quad_perm:[1,0,3,2] row_mask:0xf bank_mask:0xf bound_ctrl:1
	ds_write2st64_b32 v100, v198, v199 offset0:46 offset1:44
	v_add_f32_dpp v196, v196, v196 row_half_mirror row_mask:0xf bank_mask:0xf bound_ctrl:1
	s_nop 1
	v_add_f32_dpp v196, v196, v196 row_mirror row_mask:0xf bank_mask:0xf bound_ctrl:1
	v_mov_b32_e32 v197, v196
	s_nop 1
	v_permlane16_swap_b32_e32 v196, v197
	v_add_f32_e32 v196, v196, v197
	v_pk_fma_f32 v[82:83], v[196:197], v[168:169], v[194:195] op_sel_hi:[0,1,1] neg_lo:[1,0,0] neg_hi:[1,0,0]
	ds_read2st64_b64 v[162:165], v153 offset0:57 offset1:41
	ds_read2st64_b64 v[166:169], v153 offset0:25 offset1:73
	ds_read2_b32 v[200:201], v159 offset0:48 offset1:32
	s_waitcnt lgkmcnt(4)
	v_pk_mul_f32 v[190:191], v[82:83], v[174:175]
	v_add_f32_e32 v196, v190, v191
	v_pk_mul_f32 v[192:193], v[82:83], v[204:205]
	v_pk_mul_f32 v[194:195], v[82:83], v[176:177]
	v_add_f32_dpp v196, v196, v196 quad_perm:[1,0,3,2] row_mask:0xf bank_mask:0xf bound_ctrl:1
	v_add_f32_e32 v198, v192, v193
	v_pk_fma_f32 v[194:195], v[202:203], v[178:179], v[194:195] op_sel:[1,0,0] op_sel_hi:[1,1,1]
	v_add_f32_dpp v196, v196, v196 quad_perm:[2,3,0,1] row_mask:0xf bank_mask:0xf bound_ctrl:1
	v_add_f32_dpp v198, v198, v198 quad_perm:[1,0,3,2] row_mask:0xf bank_mask:0xf bound_ctrl:1
	s_nop 0
	v_add_f32_dpp v196, v196, v196 row_half_mirror row_mask:0xf bank_mask:0xf bound_ctrl:1
	s_nop 1
	v_add_f32_dpp v196, v196, v196 row_mirror row_mask:0xf bank_mask:0xf bound_ctrl:1
	v_mov_b32_e32 v197, v196
	s_nop 1
	v_permlane16_swap_b32_e32 v196, v197
	v_add_f32_e32 v196, v196, v197
	v_pk_fma_f32 v[82:83], v[196:197], v[180:181], v[194:195] op_sel_hi:[0,1,1] neg_lo:[1,0,0] neg_hi:[1,0,0]
	ds_read2st64_b64 v[174:177], v98 offset0:57 offset1:41
	ds_read2st64_b64 v[178:181], v98 offset0:25 offset1:73
	ds_read2_b64 v[186:189], v230 offset0:96 offset1:64
	s_waitcnt lgkmcnt(3)
	v_pk_mul_f32 v[190:191], v[82:83], v[162:163]
	v_add_f32_e32 v196, v190, v191
	v_pk_mul_f32 v[192:193], v[82:83], v[206:207]
	v_pk_mul_f32 v[194:195], v[82:83], v[164:165]
	v_add_f32_dpp v196, v196, v196 quad_perm:[1,0,3,2] row_mask:0xf bank_mask:0xf bound_ctrl:1
	v_add_f32_e32 v199, v192, v193
	v_pk_fma_f32 v[194:195], v[200:201], v[166:167], v[194:195] op_sel_hi:[0,1,1]
	v_add_f32_dpp v196, v196, v196 quad_perm:[2,3,0,1] row_mask:0xf bank_mask:0xf bound_ctrl:1
	v_add_f32_dpp v199, v199, v199 quad_perm:[1,0,3,2] row_mask:0xf bank_mask:0xf bound_ctrl:1
	ds_write2st64_b32 v100, v198, v199 offset0:42 offset1:40
	v_add_f32_dpp v196, v196, v196 row_half_mirror row_mask:0xf bank_mask:0xf bound_ctrl:1
	s_nop 1
	v_add_f32_dpp v196, v196, v196 row_mirror row_mask:0xf bank_mask:0xf bound_ctrl:1
	v_mov_b32_e32 v197, v196
	s_nop 1
	v_permlane16_swap_b32_e32 v196, v197
	v_add_f32_e32 v196, v196, v197
	v_pk_fma_f32 v[82:83], v[196:197], v[168:169], v[194:195] op_sel_hi:[0,1,1] neg_lo:[1,0,0] neg_hi:[1,0,0]
	ds_read2st64_b64 v[162:165], v153 offset0:56 offset1:40
	ds_read2st64_b64 v[166:169], v153 offset0:24 offset1:72
	ds_read2_b32 v[202:203], v159 offset0:16 offset1:0
	s_waitcnt lgkmcnt(4)
	v_pk_mul_f32 v[190:191], v[82:83], v[174:175]
	v_add_f32_e32 v196, v190, v191
	v_pk_mul_f32 v[192:193], v[82:83], v[186:187]
	v_pk_mul_f32 v[194:195], v[82:83], v[176:177]
	v_add_f32_dpp v196, v196, v196 quad_perm:[1,0,3,2] row_mask:0xf bank_mask:0xf bound_ctrl:1
	v_add_f32_e32 v198, v192, v193
	v_pk_fma_f32 v[194:195], v[200:201], v[178:179], v[194:195] op_sel:[1,0,0] op_sel_hi:[1,1,1]
	v_add_f32_dpp v196, v196, v196 quad_perm:[2,3,0,1] row_mask:0xf bank_mask:0xf bound_ctrl:1
	v_add_f32_dpp v198, v198, v198 quad_perm:[1,0,3,2] row_mask:0xf bank_mask:0xf bound_ctrl:1
	s_nop 0
	v_add_f32_dpp v196, v196, v196 row_half_mirror row_mask:0xf bank_mask:0xf bound_ctrl:1
	s_nop 1
	v_add_f32_dpp v196, v196, v196 row_mirror row_mask:0xf bank_mask:0xf bound_ctrl:1
	v_mov_b32_e32 v197, v196
	s_nop 1
	v_permlane16_swap_b32_e32 v196, v197
	v_add_f32_e32 v196, v196, v197
	v_pk_fma_f32 v[82:83], v[196:197], v[180:181], v[194:195] op_sel_hi:[0,1,1] neg_lo:[1,0,0] neg_hi:[1,0,0]
	ds_read2st64_b64 v[174:177], v98 offset0:56 offset1:40
	ds_read2st64_b64 v[178:181], v98 offset0:24 offset1:72
	ds_read2_b64 v[204:207], v230 offset0:32 offset1:0
	s_waitcnt lgkmcnt(3)
	v_pk_mul_f32 v[190:191], v[82:83], v[162:163]
	v_add_f32_e32 v196, v190, v191
	v_pk_mul_f32 v[192:193], v[82:83], v[188:189]
	v_pk_mul_f32 v[194:195], v[82:83], v[164:165]
	v_add_f32_dpp v196, v196, v196 quad_perm:[1,0,3,2] row_mask:0xf bank_mask:0xf bound_ctrl:1
	v_add_f32_e32 v199, v192, v193
	v_pk_fma_f32 v[194:195], v[202:203], v[166:167], v[194:195] op_sel_hi:[0,1,1]
	v_add_f32_dpp v196, v196, v196 quad_perm:[2,3,0,1] row_mask:0xf bank_mask:0xf bound_ctrl:1
	v_add_f32_dpp v199, v199, v199 quad_perm:[1,0,3,2] row_mask:0xf bank_mask:0xf bound_ctrl:1
	ds_write2st64_b32 v100, v198, v199 offset0:38 offset1:36
	v_add_f32_dpp v196, v196, v196 row_half_mirror row_mask:0xf bank_mask:0xf bound_ctrl:1
	s_nop 1
	v_add_f32_dpp v196, v196, v196 row_mirror row_mask:0xf bank_mask:0xf bound_ctrl:1
	v_mov_b32_e32 v197, v196
	s_nop 1
	v_permlane16_swap_b32_e32 v196, v197
	v_add_f32_e32 v196, v196, v197
	v_pk_fma_f32 v[82:83], v[196:197], v[168:169], v[194:195] op_sel_hi:[0,1,1] neg_lo:[1,0,0] neg_hi:[1,0,0]
	ds_read2st64_b64 v[162:165], v153 offset0:55 offset1:39
	ds_read2st64_b64 v[166:169], v153 offset0:23 offset1:71
	ds_read2_b32 v[200:201], v99 offset0:240 offset1:224
	s_waitcnt lgkmcnt(4)
	v_pk_mul_f32 v[190:191], v[82:83], v[174:175]
	v_add_f32_e32 v196, v190, v191
	v_pk_mul_f32 v[192:193], v[82:83], v[204:205]
	v_pk_mul_f32 v[194:195], v[82:83], v[176:177]
	v_add_f32_dpp v196, v196, v196 quad_perm:[1,0,3,2] row_mask:0xf bank_mask:0xf bound_ctrl:1
	v_add_f32_e32 v198, v192, v193
	v_pk_fma_f32 v[194:195], v[202:203], v[178:179], v[194:195] op_sel:[1,0,0] op_sel_hi:[1,1,1]
	v_add_f32_dpp v196, v196, v196 quad_perm:[2,3,0,1] row_mask:0xf bank_mask:0xf bound_ctrl:1
	v_add_f32_dpp v198, v198, v198 quad_perm:[1,0,3,2] row_mask:0xf bank_mask:0xf bound_ctrl:1
	s_nop 0
	v_add_f32_dpp v196, v196, v196 row_half_mirror row_mask:0xf bank_mask:0xf bound_ctrl:1
	s_nop 1
	v_add_f32_dpp v196, v196, v196 row_mirror row_mask:0xf bank_mask:0xf bound_ctrl:1
	v_mov_b32_e32 v197, v196
	s_nop 1
	v_permlane16_swap_b32_e32 v196, v197
	v_add_f32_e32 v196, v196, v197
	v_pk_fma_f32 v[82:83], v[196:197], v[180:181], v[194:195] op_sel_hi:[0,1,1] neg_lo:[1,0,0] neg_hi:[1,0,0]
	ds_read2st64_b64 v[174:177], v98 offset0:55 offset1:39
	ds_read2st64_b64 v[178:181], v98 offset0:23 offset1:71
	ds_read2_b64 v[186:189], v160 offset0:224 offset1:192
	s_waitcnt lgkmcnt(3)
	v_pk_mul_f32 v[190:191], v[82:83], v[162:163]
	v_add_f32_e32 v196, v190, v191
	v_pk_mul_f32 v[192:193], v[82:83], v[206:207]
	v_pk_mul_f32 v[194:195], v[82:83], v[164:165]
	v_add_f32_dpp v196, v196, v196 quad_perm:[1,0,3,2] row_mask:0xf bank_mask:0xf bound_ctrl:1
	v_add_f32_e32 v199, v192, v193
	v_pk_fma_f32 v[194:195], v[200:201], v[166:167], v[194:195] op_sel_hi:[0,1,1]
	v_add_f32_dpp v196, v196, v196 quad_perm:[2,3,0,1] row_mask:0xf bank_mask:0xf bound_ctrl:1
	v_add_f32_dpp v199, v199, v199 quad_perm:[1,0,3,2] row_mask:0xf bank_mask:0xf bound_ctrl:1
	ds_write2st64_b32 v100, v198, v199 offset0:34 offset1:32
	v_add_f32_dpp v196, v196, v196 row_half_mirror row_mask:0xf bank_mask:0xf bound_ctrl:1
	s_nop 1
	v_add_f32_dpp v196, v196, v196 row_mirror row_mask:0xf bank_mask:0xf bound_ctrl:1
	v_mov_b32_e32 v197, v196
	s_nop 1
	v_permlane16_swap_b32_e32 v196, v197
	v_add_f32_e32 v196, v196, v197
	v_pk_fma_f32 v[82:83], v[196:197], v[168:169], v[194:195] op_sel_hi:[0,1,1] neg_lo:[1,0,0] neg_hi:[1,0,0]
	ds_read2st64_b64 v[162:165], v153 offset0:54 offset1:38
	ds_read2st64_b64 v[166:169], v153 offset0:22 offset1:70
	ds_read2_b32 v[202:203], v99 offset0:208 offset1:192
	s_waitcnt lgkmcnt(4)
	v_pk_mul_f32 v[190:191], v[82:83], v[174:175]
	v_add_f32_e32 v196, v190, v191
	v_pk_mul_f32 v[192:193], v[82:83], v[186:187]
	v_pk_mul_f32 v[194:195], v[82:83], v[176:177]
	v_add_f32_dpp v196, v196, v196 quad_perm:[1,0,3,2] row_mask:0xf bank_mask:0xf bound_ctrl:1
	v_add_f32_e32 v198, v192, v193
	v_pk_fma_f32 v[194:195], v[200:201], v[178:179], v[194:195] op_sel:[1,0,0] op_sel_hi:[1,1,1]
	v_add_f32_dpp v196, v196, v196 quad_perm:[2,3,0,1] row_mask:0xf bank_mask:0xf bound_ctrl:1
	v_add_f32_dpp v198, v198, v198 quad_perm:[1,0,3,2] row_mask:0xf bank_mask:0xf bound_ctrl:1
	s_nop 0
	v_add_f32_dpp v196, v196, v196 row_half_mirror row_mask:0xf bank_mask:0xf bound_ctrl:1
	s_nop 1
	v_add_f32_dpp v196, v196, v196 row_mirror row_mask:0xf bank_mask:0xf bound_ctrl:1
	v_mov_b32_e32 v197, v196
	s_nop 1
	v_permlane16_swap_b32_e32 v196, v197
	v_add_f32_e32 v196, v196, v197
	v_pk_fma_f32 v[82:83], v[196:197], v[180:181], v[194:195] op_sel_hi:[0,1,1] neg_lo:[1,0,0] neg_hi:[1,0,0]
	ds_read2st64_b64 v[174:177], v98 offset0:54 offset1:38
	ds_read2st64_b64 v[178:181], v98 offset0:22 offset1:70
	ds_read2_b64 v[204:207], v160 offset0:160 offset1:128
	s_waitcnt lgkmcnt(3)
	v_pk_mul_f32 v[190:191], v[82:83], v[162:163]
	v_add_f32_e32 v196, v190, v191
	v_pk_mul_f32 v[192:193], v[82:83], v[188:189]
	v_pk_mul_f32 v[194:195], v[82:83], v[164:165]
	v_add_f32_dpp v196, v196, v196 quad_perm:[1,0,3,2] row_mask:0xf bank_mask:0xf bound_ctrl:1
	v_add_f32_e32 v199, v192, v193
	v_pk_fma_f32 v[194:195], v[202:203], v[166:167], v[194:195] op_sel_hi:[0,1,1]
	v_add_f32_dpp v196, v196, v196 quad_perm:[2,3,0,1] row_mask:0xf bank_mask:0xf bound_ctrl:1
	v_add_f32_dpp v199, v199, v199 quad_perm:[1,0,3,2] row_mask:0xf bank_mask:0xf bound_ctrl:1
	ds_write2st64_b32 v100, v198, v199 offset0:30 offset1:28
	v_add_f32_dpp v196, v196, v196 row_half_mirror row_mask:0xf bank_mask:0xf bound_ctrl:1
	s_nop 1
	v_add_f32_dpp v196, v196, v196 row_mirror row_mask:0xf bank_mask:0xf bound_ctrl:1
	v_mov_b32_e32 v197, v196
	s_nop 1
	v_permlane16_swap_b32_e32 v196, v197
	v_add_f32_e32 v196, v196, v197
	v_pk_fma_f32 v[82:83], v[196:197], v[168:169], v[194:195] op_sel_hi:[0,1,1] neg_lo:[1,0,0] neg_hi:[1,0,0]
	ds_read2st64_b64 v[162:165], v153 offset0:53 offset1:37
	ds_read2st64_b64 v[166:169], v153 offset0:21 offset1:69
	ds_read2_b32 v[200:201], v99 offset0:176 offset1:160
	s_waitcnt lgkmcnt(4)
	v_pk_mul_f32 v[190:191], v[82:83], v[174:175]
	v_add_f32_e32 v196, v190, v191
	v_pk_mul_f32 v[192:193], v[82:83], v[204:205]
	v_pk_mul_f32 v[194:195], v[82:83], v[176:177]
	v_add_f32_dpp v196, v196, v196 quad_perm:[1,0,3,2] row_mask:0xf bank_mask:0xf bound_ctrl:1
	v_add_f32_e32 v198, v192, v193
	v_pk_fma_f32 v[194:195], v[202:203], v[178:179], v[194:195] op_sel:[1,0,0] op_sel_hi:[1,1,1]
	v_add_f32_dpp v196, v196, v196 quad_perm:[2,3,0,1] row_mask:0xf bank_mask:0xf bound_ctrl:1
	v_add_f32_dpp v198, v198, v198 quad_perm:[1,0,3,2] row_mask:0xf bank_mask:0xf bound_ctrl:1
	s_nop 0
	v_add_f32_dpp v196, v196, v196 row_half_mirror row_mask:0xf bank_mask:0xf bound_ctrl:1
	s_nop 1
	v_add_f32_dpp v196, v196, v196 row_mirror row_mask:0xf bank_mask:0xf bound_ctrl:1
	v_mov_b32_e32 v197, v196
	s_nop 1
	v_permlane16_swap_b32_e32 v196, v197
	v_add_f32_e32 v196, v196, v197
	v_pk_fma_f32 v[82:83], v[196:197], v[180:181], v[194:195] op_sel_hi:[0,1,1] neg_lo:[1,0,0] neg_hi:[1,0,0]
	ds_read2st64_b64 v[174:177], v98 offset0:53 offset1:37
	ds_read2st64_b64 v[178:181], v98 offset0:21 offset1:69
	ds_read2_b64 v[186:189], v160 offset0:96 offset1:64
	s_waitcnt lgkmcnt(3)
	v_pk_mul_f32 v[190:191], v[82:83], v[162:163]
	v_add_f32_e32 v196, v190, v191
	v_pk_mul_f32 v[192:193], v[82:83], v[206:207]
	v_pk_mul_f32 v[194:195], v[82:83], v[164:165]
	v_add_f32_dpp v196, v196, v196 quad_perm:[1,0,3,2] row_mask:0xf bank_mask:0xf bound_ctrl:1
	v_add_f32_e32 v199, v192, v193
	v_pk_fma_f32 v[194:195], v[200:201], v[166:167], v[194:195] op_sel_hi:[0,1,1]
	v_add_f32_dpp v196, v196, v196 quad_perm:[2,3,0,1] row_mask:0xf bank_mask:0xf bound_ctrl:1
	v_add_f32_dpp v199, v199, v199 quad_perm:[1,0,3,2] row_mask:0xf bank_mask:0xf bound_ctrl:1
	ds_write2st64_b32 v100, v198, v199 offset0:26 offset1:24
	v_add_f32_dpp v196, v196, v196 row_half_mirror row_mask:0xf bank_mask:0xf bound_ctrl:1
	s_nop 1
	v_add_f32_dpp v196, v196, v196 row_mirror row_mask:0xf bank_mask:0xf bound_ctrl:1
	v_mov_b32_e32 v197, v196
	s_nop 1
	v_permlane16_swap_b32_e32 v196, v197
	v_add_f32_e32 v196, v196, v197
	v_pk_fma_f32 v[82:83], v[196:197], v[168:169], v[194:195] op_sel_hi:[0,1,1] neg_lo:[1,0,0] neg_hi:[1,0,0]
	ds_read2st64_b64 v[162:165], v153 offset0:52 offset1:36
	ds_read2st64_b64 v[166:169], v153 offset0:20 offset1:68
	ds_read2_b32 v[202:203], v99 offset0:144 offset1:128
	s_waitcnt lgkmcnt(4)
	v_pk_mul_f32 v[190:191], v[82:83], v[174:175]
	v_add_f32_e32 v196, v190, v191
	v_pk_mul_f32 v[192:193], v[82:83], v[186:187]
	v_pk_mul_f32 v[194:195], v[82:83], v[176:177]
	v_add_f32_dpp v196, v196, v196 quad_perm:[1,0,3,2] row_mask:0xf bank_mask:0xf bound_ctrl:1
	v_add_f32_e32 v198, v192, v193
	v_pk_fma_f32 v[194:195], v[200:201], v[178:179], v[194:195] op_sel:[1,0,0] op_sel_hi:[1,1,1]
	v_add_f32_dpp v196, v196, v196 quad_perm:[2,3,0,1] row_mask:0xf bank_mask:0xf bound_ctrl:1
	v_add_f32_dpp v198, v198, v198 quad_perm:[1,0,3,2] row_mask:0xf bank_mask:0xf bound_ctrl:1
	s_nop 0
	v_add_f32_dpp v196, v196, v196 row_half_mirror row_mask:0xf bank_mask:0xf bound_ctrl:1
	s_nop 1
	v_add_f32_dpp v196, v196, v196 row_mirror row_mask:0xf bank_mask:0xf bound_ctrl:1
	v_mov_b32_e32 v197, v196
	s_nop 1
	v_permlane16_swap_b32_e32 v196, v197
	v_add_f32_e32 v196, v196, v197
	v_pk_fma_f32 v[82:83], v[196:197], v[180:181], v[194:195] op_sel_hi:[0,1,1] neg_lo:[1,0,0] neg_hi:[1,0,0]
	ds_read2st64_b64 v[174:177], v98 offset0:52 offset1:36
	ds_read2st64_b64 v[178:181], v98 offset0:20 offset1:68
	ds_read2_b64 v[204:207], v160 offset0:32 offset1:0
	s_waitcnt lgkmcnt(3)
	v_pk_mul_f32 v[190:191], v[82:83], v[162:163]
	v_add_f32_e32 v196, v190, v191
	v_pk_mul_f32 v[192:193], v[82:83], v[188:189]
	v_pk_mul_f32 v[194:195], v[82:83], v[164:165]
	v_add_f32_dpp v196, v196, v196 quad_perm:[1,0,3,2] row_mask:0xf bank_mask:0xf bound_ctrl:1
	v_add_f32_e32 v199, v192, v193
	v_pk_fma_f32 v[194:195], v[202:203], v[166:167], v[194:195] op_sel_hi:[0,1,1]
	v_add_f32_dpp v196, v196, v196 quad_perm:[2,3,0,1] row_mask:0xf bank_mask:0xf bound_ctrl:1
	v_add_f32_dpp v199, v199, v199 quad_perm:[1,0,3,2] row_mask:0xf bank_mask:0xf bound_ctrl:1
	ds_write2st64_b32 v100, v198, v199 offset0:22 offset1:20
	v_add_f32_dpp v196, v196, v196 row_half_mirror row_mask:0xf bank_mask:0xf bound_ctrl:1
	s_nop 1
	v_add_f32_dpp v196, v196, v196 row_mirror row_mask:0xf bank_mask:0xf bound_ctrl:1
	v_mov_b32_e32 v197, v196
	s_nop 1
	v_permlane16_swap_b32_e32 v196, v197
	v_add_f32_e32 v196, v196, v197
	v_pk_fma_f32 v[82:83], v[196:197], v[168:169], v[194:195] op_sel_hi:[0,1,1] neg_lo:[1,0,0] neg_hi:[1,0,0]
	ds_read2st64_b64 v[162:165], v153 offset0:51 offset1:35
	ds_read2st64_b64 v[166:169], v153 offset0:19 offset1:67
	ds_read2_b32 v[200:201], v99 offset0:112 offset1:96
	s_waitcnt lgkmcnt(4)
	v_pk_mul_f32 v[190:191], v[82:83], v[174:175]
	v_add_f32_e32 v196, v190, v191
	v_pk_mul_f32 v[192:193], v[82:83], v[204:205]
	v_pk_mul_f32 v[194:195], v[82:83], v[176:177]
	v_add_f32_dpp v196, v196, v196 quad_perm:[1,0,3,2] row_mask:0xf bank_mask:0xf bound_ctrl:1
	v_add_f32_e32 v198, v192, v193
	v_pk_fma_f32 v[194:195], v[202:203], v[178:179], v[194:195] op_sel:[1,0,0] op_sel_hi:[1,1,1]
	v_add_f32_dpp v196, v196, v196 quad_perm:[2,3,0,1] row_mask:0xf bank_mask:0xf bound_ctrl:1
	v_add_f32_dpp v198, v198, v198 quad_perm:[1,0,3,2] row_mask:0xf bank_mask:0xf bound_ctrl:1
	s_nop 0
	v_add_f32_dpp v196, v196, v196 row_half_mirror row_mask:0xf bank_mask:0xf bound_ctrl:1
	s_nop 1
	v_add_f32_dpp v196, v196, v196 row_mirror row_mask:0xf bank_mask:0xf bound_ctrl:1
	v_mov_b32_e32 v197, v196
	s_nop 1
	v_permlane16_swap_b32_e32 v196, v197
	v_add_f32_e32 v196, v196, v197
	v_pk_fma_f32 v[82:83], v[196:197], v[180:181], v[194:195] op_sel_hi:[0,1,1] neg_lo:[1,0,0] neg_hi:[1,0,0]
	ds_read2st64_b64 v[174:177], v98 offset0:51 offset1:35
	ds_read2st64_b64 v[178:181], v98 offset0:19 offset1:67
	ds_read2_b64 v[186:189], v98 offset0:224 offset1:192
	s_waitcnt lgkmcnt(3)
	v_pk_mul_f32 v[190:191], v[82:83], v[162:163]
	v_add_f32_e32 v196, v190, v191
	v_pk_mul_f32 v[192:193], v[82:83], v[206:207]
	v_pk_mul_f32 v[194:195], v[82:83], v[164:165]
	v_add_f32_dpp v196, v196, v196 quad_perm:[1,0,3,2] row_mask:0xf bank_mask:0xf bound_ctrl:1
	v_add_f32_e32 v199, v192, v193
	v_pk_fma_f32 v[194:195], v[200:201], v[166:167], v[194:195] op_sel_hi:[0,1,1]
	v_add_f32_dpp v196, v196, v196 quad_perm:[2,3,0,1] row_mask:0xf bank_mask:0xf bound_ctrl:1
	v_add_f32_dpp v199, v199, v199 quad_perm:[1,0,3,2] row_mask:0xf bank_mask:0xf bound_ctrl:1
	ds_write2st64_b32 v100, v198, v199 offset0:18 offset1:16
	v_add_f32_dpp v196, v196, v196 row_half_mirror row_mask:0xf bank_mask:0xf bound_ctrl:1
	s_nop 1
	v_add_f32_dpp v196, v196, v196 row_mirror row_mask:0xf bank_mask:0xf bound_ctrl:1
	v_mov_b32_e32 v197, v196
	s_nop 1
	v_permlane16_swap_b32_e32 v196, v197
	v_add_f32_e32 v196, v196, v197
	v_pk_fma_f32 v[82:83], v[196:197], v[168:169], v[194:195] op_sel_hi:[0,1,1] neg_lo:[1,0,0] neg_hi:[1,0,0]
	ds_read2st64_b64 v[162:165], v153 offset0:50 offset1:34
	ds_read2st64_b64 v[166:169], v153 offset0:18 offset1:66
	ds_read2_b32 v[202:203], v99 offset0:80 offset1:64
	s_waitcnt lgkmcnt(4)
	v_pk_mul_f32 v[190:191], v[82:83], v[174:175]
	v_add_f32_e32 v196, v190, v191
	v_pk_mul_f32 v[192:193], v[82:83], v[186:187]
	v_pk_mul_f32 v[194:195], v[82:83], v[176:177]
	v_add_f32_dpp v196, v196, v196 quad_perm:[1,0,3,2] row_mask:0xf bank_mask:0xf bound_ctrl:1
	v_add_f32_e32 v198, v192, v193
	v_pk_fma_f32 v[194:195], v[200:201], v[178:179], v[194:195] op_sel:[1,0,0] op_sel_hi:[1,1,1]
	v_add_f32_dpp v196, v196, v196 quad_perm:[2,3,0,1] row_mask:0xf bank_mask:0xf bound_ctrl:1
	v_add_f32_dpp v198, v198, v198 quad_perm:[1,0,3,2] row_mask:0xf bank_mask:0xf bound_ctrl:1
	s_nop 0
	v_add_f32_dpp v196, v196, v196 row_half_mirror row_mask:0xf bank_mask:0xf bound_ctrl:1
	s_nop 1
	v_add_f32_dpp v196, v196, v196 row_mirror row_mask:0xf bank_mask:0xf bound_ctrl:1
	v_mov_b32_e32 v197, v196
	s_nop 1
	v_permlane16_swap_b32_e32 v196, v197
	v_add_f32_e32 v196, v196, v197
	v_pk_fma_f32 v[82:83], v[196:197], v[180:181], v[194:195] op_sel_hi:[0,1,1] neg_lo:[1,0,0] neg_hi:[1,0,0]
	ds_read2st64_b64 v[174:177], v98 offset0:50 offset1:34
	ds_read2st64_b64 v[178:181], v98 offset0:18 offset1:66
	ds_read2_b64 v[204:207], v98 offset0:160 offset1:128
	s_waitcnt lgkmcnt(3)
	v_pk_mul_f32 v[190:191], v[82:83], v[162:163]
	v_add_f32_e32 v196, v190, v191
	v_pk_mul_f32 v[192:193], v[82:83], v[188:189]
	v_pk_mul_f32 v[194:195], v[82:83], v[164:165]
	v_add_f32_dpp v196, v196, v196 quad_perm:[1,0,3,2] row_mask:0xf bank_mask:0xf bound_ctrl:1
	v_add_f32_e32 v199, v192, v193
	v_pk_fma_f32 v[194:195], v[202:203], v[166:167], v[194:195] op_sel_hi:[0,1,1]
	v_add_f32_dpp v196, v196, v196 quad_perm:[2,3,0,1] row_mask:0xf bank_mask:0xf bound_ctrl:1
	v_add_f32_dpp v199, v199, v199 quad_perm:[1,0,3,2] row_mask:0xf bank_mask:0xf bound_ctrl:1
	ds_write2st64_b32 v100, v198, v199 offset0:14 offset1:12
	v_add_f32_dpp v196, v196, v196 row_half_mirror row_mask:0xf bank_mask:0xf bound_ctrl:1
	s_nop 1
	v_add_f32_dpp v196, v196, v196 row_mirror row_mask:0xf bank_mask:0xf bound_ctrl:1
	v_mov_b32_e32 v197, v196
	s_nop 1
	v_permlane16_swap_b32_e32 v196, v197
	v_add_f32_e32 v196, v196, v197
	v_pk_fma_f32 v[82:83], v[196:197], v[168:169], v[194:195] op_sel_hi:[0,1,1] neg_lo:[1,0,0] neg_hi:[1,0,0]
	ds_read2st64_b64 v[162:165], v153 offset0:49 offset1:33
	ds_read2st64_b64 v[166:169], v153 offset0:17 offset1:65
	ds_read2_b32 v[200:201], v99 offset0:48 offset1:32
	s_waitcnt lgkmcnt(4)
	v_pk_mul_f32 v[190:191], v[82:83], v[174:175]
	v_add_f32_e32 v196, v190, v191
	v_pk_mul_f32 v[192:193], v[82:83], v[204:205]
	v_pk_mul_f32 v[194:195], v[82:83], v[176:177]
	v_add_f32_dpp v196, v196, v196 quad_perm:[1,0,3,2] row_mask:0xf bank_mask:0xf bound_ctrl:1
	v_add_f32_e32 v198, v192, v193
	v_pk_fma_f32 v[194:195], v[202:203], v[178:179], v[194:195] op_sel:[1,0,0] op_sel_hi:[1,1,1]
	v_add_f32_dpp v196, v196, v196 quad_perm:[2,3,0,1] row_mask:0xf bank_mask:0xf bound_ctrl:1
	v_add_f32_dpp v198, v198, v198 quad_perm:[1,0,3,2] row_mask:0xf bank_mask:0xf bound_ctrl:1
	s_nop 0
	v_add_f32_dpp v196, v196, v196 row_half_mirror row_mask:0xf bank_mask:0xf bound_ctrl:1
	s_nop 1
	v_add_f32_dpp v196, v196, v196 row_mirror row_mask:0xf bank_mask:0xf bound_ctrl:1
	v_mov_b32_e32 v197, v196
	s_nop 1
	v_permlane16_swap_b32_e32 v196, v197
	v_add_f32_e32 v196, v196, v197
	v_pk_fma_f32 v[82:83], v[196:197], v[180:181], v[194:195] op_sel_hi:[0,1,1] neg_lo:[1,0,0] neg_hi:[1,0,0]
	ds_read2st64_b64 v[174:177], v98 offset0:49 offset1:33
	ds_read2st64_b64 v[178:181], v98 offset0:17 offset1:65
	ds_read2_b64 v[186:189], v98 offset0:96 offset1:64
	s_waitcnt lgkmcnt(3)
	v_pk_mul_f32 v[190:191], v[82:83], v[162:163]
	v_add_f32_e32 v196, v190, v191
	v_pk_mul_f32 v[192:193], v[82:83], v[206:207]
	v_pk_mul_f32 v[194:195], v[82:83], v[164:165]
	v_add_f32_dpp v196, v196, v196 quad_perm:[1,0,3,2] row_mask:0xf bank_mask:0xf bound_ctrl:1
	v_add_f32_e32 v199, v192, v193
	v_pk_fma_f32 v[194:195], v[200:201], v[166:167], v[194:195] op_sel_hi:[0,1,1]
	v_add_f32_dpp v196, v196, v196 quad_perm:[2,3,0,1] row_mask:0xf bank_mask:0xf bound_ctrl:1
	v_add_f32_dpp v199, v199, v199 quad_perm:[1,0,3,2] row_mask:0xf bank_mask:0xf bound_ctrl:1
	ds_write2st64_b32 v100, v198, v199 offset0:10 offset1:8
	v_add_f32_dpp v196, v196, v196 row_half_mirror row_mask:0xf bank_mask:0xf bound_ctrl:1
	s_nop 1
	v_add_f32_dpp v196, v196, v196 row_mirror row_mask:0xf bank_mask:0xf bound_ctrl:1
	v_mov_b32_e32 v197, v196
	s_nop 1
	v_permlane16_swap_b32_e32 v196, v197
	v_add_f32_e32 v196, v196, v197
	v_pk_fma_f32 v[82:83], v[196:197], v[168:169], v[194:195] op_sel_hi:[0,1,1] neg_lo:[1,0,0] neg_hi:[1,0,0]
	ds_read2st64_b64 v[162:165], v153 offset0:48 offset1:32
	ds_read2st64_b64 v[166:169], v153 offset0:16 offset1:64
	ds_read2_b32 v[202:203], v99 offset0:16 offset1:0
	s_waitcnt lgkmcnt(4)
	v_pk_mul_f32 v[190:191], v[82:83], v[174:175]
	v_add_f32_e32 v196, v190, v191
	v_pk_mul_f32 v[192:193], v[82:83], v[186:187]
	v_pk_mul_f32 v[194:195], v[82:83], v[176:177]
	v_add_f32_dpp v196, v196, v196 quad_perm:[1,0,3,2] row_mask:0xf bank_mask:0xf bound_ctrl:1
	v_add_f32_e32 v198, v192, v193
	v_pk_fma_f32 v[194:195], v[200:201], v[178:179], v[194:195] op_sel:[1,0,0] op_sel_hi:[1,1,1]
	v_add_f32_dpp v196, v196, v196 quad_perm:[2,3,0,1] row_mask:0xf bank_mask:0xf bound_ctrl:1
	v_add_f32_dpp v198, v198, v198 quad_perm:[1,0,3,2] row_mask:0xf bank_mask:0xf bound_ctrl:1
	s_nop 0
	v_add_f32_dpp v196, v196, v196 row_half_mirror row_mask:0xf bank_mask:0xf bound_ctrl:1
	s_nop 1
	v_add_f32_dpp v196, v196, v196 row_mirror row_mask:0xf bank_mask:0xf bound_ctrl:1
	v_mov_b32_e32 v197, v196
	s_nop 1
	v_permlane16_swap_b32_e32 v196, v197
	v_add_f32_e32 v196, v196, v197
	v_pk_fma_f32 v[82:83], v[196:197], v[180:181], v[194:195] op_sel_hi:[0,1,1] neg_lo:[1,0,0] neg_hi:[1,0,0]
	ds_read2st64_b64 v[174:177], v98 offset0:48 offset1:32
	ds_read2st64_b64 v[178:181], v98 offset0:16 offset1:64
	ds_read2_b64 v[204:207], v98 offset0:32 offset1:0
	s_waitcnt lgkmcnt(3)
	v_pk_mul_f32 v[190:191], v[82:83], v[162:163]
	v_add_f32_e32 v196, v190, v191
	v_pk_mul_f32 v[192:193], v[82:83], v[188:189]
	v_pk_mul_f32 v[194:195], v[82:83], v[164:165]
	v_add_f32_dpp v196, v196, v196 quad_perm:[1,0,3,2] row_mask:0xf bank_mask:0xf bound_ctrl:1
	v_add_f32_e32 v199, v192, v193
	v_pk_fma_f32 v[194:195], v[202:203], v[166:167], v[194:195] op_sel_hi:[0,1,1]
	v_add_f32_dpp v196, v196, v196 quad_perm:[2,3,0,1] row_mask:0xf bank_mask:0xf bound_ctrl:1
	v_add_f32_dpp v199, v199, v199 quad_perm:[1,0,3,2] row_mask:0xf bank_mask:0xf bound_ctrl:1
	ds_write2st64_b32 v100, v198, v199 offset0:6 offset1:4
	v_add_f32_dpp v196, v196, v196 row_half_mirror row_mask:0xf bank_mask:0xf bound_ctrl:1
	s_nop 1
	v_add_f32_dpp v196, v196, v196 row_mirror row_mask:0xf bank_mask:0xf bound_ctrl:1
	v_mov_b32_e32 v197, v196
	s_nop 1
	v_permlane16_swap_b32_e32 v196, v197
	v_add_f32_e32 v196, v196, v197
	v_pk_fma_f32 v[82:83], v[196:197], v[168:169], v[194:195] op_sel_hi:[0,1,1] neg_lo:[1,0,0] neg_hi:[1,0,0]
	s_waitcnt lgkmcnt(1)
	v_pk_mul_f32 v[190:191], v[82:83], v[174:175]
	v_add_f32_e32 v196, v190, v191
	v_pk_mul_f32 v[192:193], v[82:83], v[204:205]
	v_pk_mul_f32 v[194:195], v[82:83], v[176:177]
	v_add_f32_dpp v196, v196, v196 quad_perm:[1,0,3,2] row_mask:0xf bank_mask:0xf bound_ctrl:1
	v_add_f32_e32 v198, v192, v193
	v_pk_fma_f32 v[194:195], v[202:203], v[178:179], v[194:195] op_sel:[1,0,0] op_sel_hi:[1,1,1]
	v_add_f32_dpp v196, v196, v196 quad_perm:[2,3,0,1] row_mask:0xf bank_mask:0xf bound_ctrl:1
	v_add_f32_dpp v198, v198, v198 quad_perm:[1,0,3,2] row_mask:0xf bank_mask:0xf bound_ctrl:1
	s_nop 0
	v_add_f32_dpp v196, v196, v196 row_half_mirror row_mask:0xf bank_mask:0xf bound_ctrl:1
	s_nop 1
	v_add_f32_dpp v196, v196, v196 row_mirror row_mask:0xf bank_mask:0xf bound_ctrl:1
	v_mov_b32_e32 v197, v196
	s_nop 1
	v_permlane16_swap_b32_e32 v196, v197
	v_add_f32_e32 v196, v196, v197
	v_pk_fma_f32 v[82:83], v[196:197], v[180:181], v[194:195] op_sel_hi:[0,1,1] neg_lo:[1,0,0] neg_hi:[1,0,0]
	v_pk_mul_f32 v[192:193], v[82:83], v[206:207]
	v_add_f32_e32 v199, v192, v193
	s_nop 1
	v_add_f32_dpp v199, v199, v199 quad_perm:[1,0,3,2] row_mask:0xf bank_mask:0xf bound_ctrl:1
	ds_write2st64_b32 v100, v198, v199 offset0:2 offset1:0
	s_branch .Lrs_post
.Lrs_fwd:
	ds_read2st64_b64 v[162:165], v98 offset0:48 offset1:32
	ds_read2st64_b64 v[166:169], v98 offset0:16 offset1:64
	ds_read2_b32 v[200:201], v99 offset0:0 offset1:16
	ds_read2st64_b64 v[174:177], v153 offset0:48 offset1:32
	ds_read2st64_b64 v[178:181], v153 offset0:16 offset1:64
	ds_read2_b64 v[186:189], v98 offset0:0 offset1:32
	s_waitcnt lgkmcnt(3)
	v_pk_mul_f32 v[190:191], v[82:83], v[162:163]
	v_add_f32_e32 v196, v190, v191
	v_pk_mul_f32 v[194:195], v[82:83], v[164:165]
	s_nop 0
	v_add_f32_dpp v196, v196, v196 quad_perm:[1,0,3,2] row_mask:0xf bank_mask:0xf bound_ctrl:1
	v_pk_fma_f32 v[194:195], v[200:201], v[166:167], v[194:195] op_sel_hi:[0,1,1]
	s_nop 0
	v_add_f32_dpp v196, v196, v196 quad_perm:[2,3,0,1] row_mask:0xf bank_mask:0xf bound_ctrl:1
	s_nop 1
	v_add_f32_dpp v196, v196, v196 row_half_mirror row_mask:0xf bank_mask:0xf bound_ctrl:1
	s_nop 1
	v_add_f32_dpp v196, v196, v196 row_mirror row_mask:0xf bank_mask:0xf bound_ctrl:1
	v_mov_b32_e32 v197, v196
	s_nop 1
	v_permlane16_swap_b32_e32 v196, v197
	v_add_f32_e32 v196, v196, v197
	v_pk_fma_f32 v[82:83], v[196:197], v[168:169], v[194:195] op_sel_hi:[0,1,1] neg_lo:[1,0,0] neg_hi:[1,0,0]
	ds_read2st64_b64 v[162:165], v98 offset0:49 offset1:33
	ds_read2st64_b64 v[166:169], v98 offset0:17 offset1:65
	ds_read2_b32 v[202:203], v99 offset0:32 offset1:48
	s_waitcnt lgkmcnt(3)
	v_pk_mul_f32 v[190:191], v[82:83], v[174:175]
	v_add_f32_e32 v196, v190, v191
	v_pk_mul_f32 v[192:193], v[82:83], v[186:187]
	v_pk_mul_f32 v[194:195], v[82:83], v[176:177]
	v_add_f32_dpp v196, v196, v196 quad_perm:[1,0,3,2] row_mask:0xf bank_mask:0xf bound_ctrl:1
	v_add_f32_e32 v198, v192, v193
	v_pk_fma_f32 v[194:195], v[200:201], v[178:179], v[194:195] op_sel:[1,0,0] op_sel_hi:[1,1,1]
	v_add_f32_dpp v196, v196, v196 quad_perm:[2,3,0,1] row_mask:0xf bank_mask:0xf bound_ctrl:1
	v_add_f32_dpp v198, v198, v198 quad_perm:[1,0,3,2] row_mask:0xf bank_mask:0xf bound_ctrl:1
	s_nop 0
	v_add_f32_dpp v196, v196, v196 row_half_mirror row_mask:0xf bank_mask:0xf bound_ctrl:1
	s_nop 1
	v_add_f32_dpp v196, v196, v196 row_mirror row_mask:0xf bank_mask:0xf bound_ctrl:1
	v_mov_b32_e32 v197, v196
	s_nop 1
	v_permlane16_swap_b32_e32 v196, v197
	v_add_f32_e32 v196, v196, v197
	v_pk_fma_f32 v[82:83], v[196:197], v[180:181], v[194:195] op_sel_hi:[0,1,1] neg_lo:[1,0,0] neg_hi:[1,0,0]
	ds_read2st64_b64 v[174:177], v153 offset0:49 offset1:33
	ds_read2st64_b64 v[178:181], v153 offset0:17 offset1:65
	ds_read2_b64 v[204:207], v98 offset0:64 offset1:96
	s_waitcnt lgkmcnt(3)
	v_pk_mul_f32 v[190:191], v[82:83], v[162:163]
	v_add_f32_e32 v196, v190, v191
	v_pk_mul_f32 v[192:193], v[82:83], v[188:189]
	v_pk_mul_f32 v[194:195], v[82:83], v[164:165]
	v_add_f32_dpp v196, v196, v196 quad_perm:[1,0,3,2] row_mask:0xf bank_mask:0xf bound_ctrl:1
	v_add_f32_e32 v199, v192, v193
	v_pk_fma_f32 v[194:195], v[202:203], v[166:167], v[194:195] op_sel_hi:[0,1,1]
	v_add_f32_dpp v196, v196, v196 quad_perm:[2,3,0,1] row_mask:0xf bank_mask:0xf bound_ctrl:1
	v_add_f32_dpp v199, v199, v199 quad_perm:[1,0,3,2] row_mask:0xf bank_mask:0xf bound_ctrl:1
	ds_write2st64_b32 v100, v198, v199 offset0:0 offset1:2
	v_add_f32_dpp v196, v196, v196 row_half_mirror row_mask:0xf bank_mask:0xf bound_ctrl:1
	s_nop 1
	v_add_f32_dpp v196, v196, v196 row_mirror row_mask:0xf bank_mask:0xf bound_ctrl:1
	v_mov_b32_e32 v197, v196
	s_nop 1
	v_permlane16_swap_b32_e32 v196, v197
	v_add_f32_e32 v196, v196, v197
	v_pk_fma_f32 v[82:83], v[196:197], v[168:169], v[194:195] op_sel_hi:[0,1,1] neg_lo:[1,0,0] neg_hi:[1,0,0]
	ds_read2st64_b64 v[162:165], v98 offset0:50 offset1:34
	ds_read2st64_b64 v[166:169], v98 offset0:18 offset1:66
	ds_read2_b32 v[200:201], v99 offset0:64 offset1:80
	s_waitcnt lgkmcnt(4)
	v_pk_mul_f32 v[190:191], v[82:83], v[174:175]
	v_add_f32_e32 v196, v190, v191
	v_pk_mul_f32 v[192:193], v[82:83], v[204:205]
	v_pk_mul_f32 v[194:195], v[82:83], v[176:177]
	v_add_f32_dpp v196, v196, v196 quad_perm:[1,0,3,2] row_mask:0xf bank_mask:0xf bound_ctrl:1
	v_add_f32_e32 v198, v192, v193
	v_pk_fma_f32 v[194:195], v[202:203], v[178:179], v[194:195] op_sel:[1,0,0] op_sel_hi:[1,1,1]
	v_add_f32_dpp v196, v196, v196 quad_perm:[2,3,0,1] row_mask:0xf bank_mask:0xf bound_ctrl:1
	v_add_f32_dpp v198, v198, v198 quad_perm:[1,0,3,2] row_mask:0xf bank_mask:0xf bound_ctrl:1
	s_nop 0
	v_add_f32_dpp v196, v196, v196 row_half_mirror row_mask:0xf bank_mask:0xf bound_ctrl:1
	s_nop 1
	v_add_f32_dpp v196, v196, v196 row_mirror row_mask:0xf bank_mask:0xf bound_ctrl:1
	v_mov_b32_e32 v197, v196
	s_nop 1
	v_permlane16_swap_b32_e32 v196, v197
	v_add_f32_e32 v196, v196, v197
	v_pk_fma_f32 v[82:83], v[196:197], v[180:181], v[194:195] op_sel_hi:[0,1,1] neg_lo:[1,0,0] neg_hi:[1,0,0]
	ds_read2st64_b64 v[174:177], v153 offset0:50 offset1:34
	ds_read2st64_b64 v[178:181], v153 offset0:18 offset1:66
	ds_read2_b64 v[186:189], v98 offset0:128 offset1:160
	s_waitcnt lgkmcnt(3)
	v_pk_mul_f32 v[190:191], v[82:83], v[162:163]
	v_add_f32_e32 v196, v190, v191
	v_pk_mul_f32 v[192:193], v[82:83], v[206:207]
	v_pk_mul_f32 v[194:195], v[82:83], v[164:165]
	v_add_f32_dpp v196, v196, v196 quad_perm:[1,0,3,2] row_mask:0xf bank_mask:0xf bound_ctrl:1
	v_add_f32_e32 v199, v192, v193
	v_pk_fma_f32 v[194:195], v[200:201], v[166:167], v[194:195] op_sel_hi:[0,1,1]
	v_add_f32_dpp v196, v196, v196 quad_perm:[2,3,0,1] row_mask:0xf bank_mask:0xf bound_ctrl:1
	v_add_f32_dpp v199, v199, v199 quad_perm:[1,0,3,2] row_mask:0xf bank_mask:0xf bound_ctrl:1
	ds_write2st64_b32 v100, v198, v199 offset0:4 offset1:6
	v_add_f32_dpp v196, v196, v196 row_half_mirror row_mask:0xf bank_mask:0xf bound_ctrl:1
	s_nop 1
	v_add_f32_dpp v196, v196, v196 row_mirror row_mask:0xf bank_mask:0xf bound_ctrl:1
	v_mov_b32_e32 v197, v196
	s_nop 1
	v_permlane16_swap_b32_e32 v196, v197
	v_add_f32_e32 v196, v196, v197
	v_pk_fma_f32 v[82:83], v[196:197], v[168:169], v[194:195] op_sel_hi:[0,1,1] neg_lo:[1,0,0] neg_hi:[1,0,0]
	ds_read2st64_b64 v[162:165], v98 offset0:51 offset1:35
	ds_read2st64_b64 v[166:169], v98 offset0:19 offset1:67
	ds_read2_b32 v[202:203], v99 offset0:96 offset1:112
	s_waitcnt lgkmcnt(4)
	v_pk_mul_f32 v[190:191], v[82:83], v[174:175]
	v_add_f32_e32 v196, v190, v191
	v_pk_mul_f32 v[192:193], v[82:83], v[186:187]
	v_pk_mul_f32 v[194:195], v[82:83], v[176:177]
	v_add_f32_dpp v196, v196, v196 quad_perm:[1,0,3,2] row_mask:0xf bank_mask:0xf bound_ctrl:1
	v_add_f32_e32 v198, v192, v193
	v_pk_fma_f32 v[194:195], v[200:201], v[178:179], v[194:195] op_sel:[1,0,0] op_sel_hi:[1,1,1]
	v_add_f32_dpp v196, v196, v196 quad_perm:[2,3,0,1] row_mask:0xf bank_mask:0xf bound_ctrl:1
	v_add_f32_dpp v198, v198, v198 quad_perm:[1,0,3,2] row_mask:0xf bank_mask:0xf bound_ctrl:1
	s_nop 0
	v_add_f32_dpp v196, v196, v196 row_half_mirror row_mask:0xf bank_mask:0xf bound_ctrl:1
	s_nop 1
	v_add_f32_dpp v196, v196, v196 row_mirror row_mask:0xf bank_mask:0xf bound_ctrl:1
	v_mov_b32_e32 v197, v196
	s_nop 1
	v_permlane16_swap_b32_e32 v196, v197
	v_add_f32_e32 v196, v196, v197
	v_pk_fma_f32 v[82:83], v[196:197], v[180:181], v[194:195] op_sel_hi:[0,1,1] neg_lo:[1,0,0] neg_hi:[1,0,0]
	ds_read2st64_b64 v[174:177], v153 offset0:51 offset1:35
	ds_read2st64_b64 v[178:181], v153 offset0:19 offset1:67
	ds_read2_b64 v[204:207], v98 offset0:192 offset1:224
	s_waitcnt lgkmcnt(3)
	v_pk_mul_f32 v[190:191], v[82:83], v[162:163]
	v_add_f32_e32 v196, v190, v191
	v_pk_mul_f32 v[192:193], v[82:83], v[188:189]
	v_pk_mul_f32 v[194:195], v[82:83], v[164:165]
	v_add_f32_dpp v196, v196, v196 quad_perm:[1,0,3,2] row_mask:0xf bank_mask:0xf bound_ctrl:1
	v_add_f32_e32 v199, v192, v193
	v_pk_fma_f32 v[194:195], v[202:203], v[166:167], v[194:195] op_sel_hi:[0,1,1]
	v_add_f32_dpp v196, v196, v196 quad_perm:[2,3,0,1] row_mask:0xf bank_mask:0xf bound_ctrl:1
	v_add_f32_dpp v199, v199, v199 quad_perm:[1,0,3,2] row_mask:0xf bank_mask:0xf bound_ctrl:1
	ds_write2st64_b32 v100, v198, v199 offset0:8 offset1:10
	v_add_f32_dpp v196, v196, v196 row_half_mirror row_mask:0xf bank_mask:0xf bound_ctrl:1
	s_nop 1
	v_add_f32_dpp v196, v196, v196 row_mirror row_mask:0xf bank_mask:0xf bound_ctrl:1
	v_mov_b32_e32 v197, v196
	s_nop 1
	v_permlane16_swap_b32_e32 v196, v197
	v_add_f32_e32 v196, v196, v197
	v_pk_fma_f32 v[82:83], v[196:197], v[168:169], v[194:195] op_sel_hi:[0,1,1] neg_lo:[1,0,0] neg_hi:[1,0,0]
	ds_read2st64_b64 v[162:165], v98 offset0:52 offset1:36
	ds_read2st64_b64 v[166:169], v98 offset0:20 offset1:68
	ds_read2_b32 v[200:201], v99 offset0:128 offset1:144
	s_waitcnt lgkmcnt(4)
	v_pk_mul_f32 v[190:191], v[82:83], v[174:175]
	v_add_f32_e32 v196, v190, v191
	v_pk_mul_f32 v[192:193], v[82:83], v[204:205]
	v_pk_mul_f32 v[194:195], v[82:83], v[176:177]
	v_add_f32_dpp v196, v196, v196 quad_perm:[1,0,3,2] row_mask:0xf bank_mask:0xf bound_ctrl:1
	v_add_f32_e32 v198, v192, v193
	v_pk_fma_f32 v[194:195], v[202:203], v[178:179], v[194:195] op_sel:[1,0,0] op_sel_hi:[1,1,1]
	v_add_f32_dpp v196, v196, v196 quad_perm:[2,3,0,1] row_mask:0xf bank_mask:0xf bound_ctrl:1
	v_add_f32_dpp v198, v198, v198 quad_perm:[1,0,3,2] row_mask:0xf bank_mask:0xf bound_ctrl:1
	s_nop 0
	v_add_f32_dpp v196, v196, v196 row_half_mirror row_mask:0xf bank_mask:0xf bound_ctrl:1
	s_nop 1
	v_add_f32_dpp v196, v196, v196 row_mirror row_mask:0xf bank_mask:0xf bound_ctrl:1
	v_mov_b32_e32 v197, v196
	s_nop 1
	v_permlane16_swap_b32_e32 v196, v197
	v_add_f32_e32 v196, v196, v197
	v_pk_fma_f32 v[82:83], v[196:197], v[180:181], v[194:195] op_sel_hi:[0,1,1] neg_lo:[1,0,0] neg_hi:[1,0,0]
	ds_read2st64_b64 v[174:177], v153 offset0:52 offset1:36
	ds_read2st64_b64 v[178:181], v153 offset0:20 offset1:68
	ds_read2_b64 v[186:189], v160 offset0:0 offset1:32
	s_waitcnt lgkmcnt(3)
	v_pk_mul_f32 v[190:191], v[82:83], v[162:163]
	v_add_f32_e32 v196, v190, v191
	v_pk_mul_f32 v[192:193], v[82:83], v[206:207]
	v_pk_mul_f32 v[194:195], v[82:83], v[164:165]
	v_add_f32_dpp v196, v196, v196 quad_perm:[1,0,3,2] row_mask:0xf bank_mask:0xf bound_ctrl:1
	v_add_f32_e32 v199, v192, v193
	v_pk_fma_f32 v[194:195], v[200:201], v[166:167], v[194:195] op_sel_hi:[0,1,1]
	v_add_f32_dpp v196, v196, v196 quad_perm:[2,3,0,1] row_mask:0xf bank_mask:0xf bound_ctrl:1
	v_add_f32_dpp v199, v199, v199 quad_perm:[1,0,3,2] row_mask:0xf bank_mask:0xf bound_ctrl:1
	ds_write2st64_b32 v100, v198, v199 offset0:12 offset1:14
	v_add_f32_dpp v196, v196, v196 row_half_mirror row_mask:0xf bank_mask:0xf bound_ctrl:1
	s_nop 1
	v_add_f32_dpp v196, v196, v196 row_mirror row_mask:0xf bank_mask:0xf bound_ctrl:1
	v_mov_b32_e32 v197, v196
	s_nop 1
	v_permlane16_swap_b32_e32 v196, v197
	v_add_f32_e32 v196, v196, v197
	v_pk_fma_f32 v[82:83], v[196:197], v[168:169], v[194:195] op_sel_hi:[0,1,1] neg_lo:[1,0,0] neg_hi:[1,0,0]
	ds_read2st64_b64 v[162:165], v98 offset0:53 offset1:37
	ds_read2st64_b64 v[166:169], v98 offset0:21 offset1:69
	ds_read2_b32 v[202:203], v99 offset0:160 offset1:176
	s_waitcnt lgkmcnt(4)
	v_pk_mul_f32 v[190:191], v[82:83], v[174:175]
	v_add_f32_e32 v196, v190, v191
	v_pk_mul_f32 v[192:193], v[82:83], v[186:187]
	v_pk_mul_f32 v[194:195], v[82:83], v[176:177]
	v_add_f32_dpp v196, v196, v196 quad_perm:[1,0,3,2] row_mask:0xf bank_mask:0xf bound_ctrl:1
	v_add_f32_e32 v198, v192, v193
	v_pk_fma_f32 v[194:195], v[200:201], v[178:179], v[194:195] op_sel:[1,0,0] op_sel_hi:[1,1,1]
	v_add_f32_dpp v196, v196, v196 quad_perm:[2,3,0,1] row_mask:0xf bank_mask:0xf bound_ctrl:1
	v_add_f32_dpp v198, v198, v198 quad_perm:[1,0,3,2] row_mask:0xf bank_mask:0xf bound_ctrl:1
	s_nop 0
	v_add_f32_dpp v196, v196, v196 row_half_mirror row_mask:0xf bank_mask:0xf bound_ctrl:1
	s_nop 1
	v_add_f32_dpp v196, v196, v196 row_mirror row_mask:0xf bank_mask:0xf bound_ctrl:1
	v_mov_b32_e32 v197, v196
	s_nop 1
	v_permlane16_swap_b32_e32 v196, v197
	v_add_f32_e32 v196, v196, v197
	v_pk_fma_f32 v[82:83], v[196:197], v[180:181], v[194:195] op_sel_hi:[0,1,1] neg_lo:[1,0,0] neg_hi:[1,0,0]
	ds_read2st64_b64 v[174:177], v153 offset0:53 offset1:37
	ds_read2st64_b64 v[178:181], v153 offset0:21 offset1:69
	ds_read2_b64 v[204:207], v160 offset0:64 offset1:96
	s_waitcnt lgkmcnt(3)
	v_pk_mul_f32 v[190:191], v[82:83], v[162:163]
	v_add_f32_e32 v196, v190, v191
	v_pk_mul_f32 v[192:193], v[82:83], v[188:189]
	v_pk_mul_f32 v[194:195], v[82:83], v[164:165]
	v_add_f32_dpp v196, v196, v196 quad_perm:[1,0,3,2] row_mask:0xf bank_mask:0xf bound_ctrl:1
	v_add_f32_e32 v199, v192, v193
	v_pk_fma_f32 v[194:195], v[202:203], v[166:167], v[194:195] op_sel_hi:[0,1,1]
	v_add_f32_dpp v196, v196, v196 quad_perm:[2,3,0,1] row_mask:0xf bank_mask:0xf bound_ctrl:1
	v_add_f32_dpp v199, v199, v199 quad_perm:[1,0,3,2] row_mask:0xf bank_mask:0xf bound_ctrl:1
	ds_write2st64_b32 v100, v198, v199 offset0:16 offset1:18
	v_add_f32_dpp v196, v196, v196 row_half_mirror row_mask:0xf bank_mask:0xf bound_ctrl:1
	s_nop 1
	v_add_f32_dpp v196, v196, v196 row_mirror row_mask:0xf bank_mask:0xf bound_ctrl:1
	v_mov_b32_e32 v197, v196
	s_nop 1
	v_permlane16_swap_b32_e32 v196, v197
	v_add_f32_e32 v196, v196, v197
	v_pk_fma_f32 v[82:83], v[196:197], v[168:169], v[194:195] op_sel_hi:[0,1,1] neg_lo:[1,0,0] neg_hi:[1,0,0]
	ds_read2st64_b64 v[162:165], v98 offset0:54 offset1:38
	ds_read2st64_b64 v[166:169], v98 offset0:22 offset1:70
	ds_read2_b32 v[200:201], v99 offset0:192 offset1:208
	s_waitcnt lgkmcnt(4)
	v_pk_mul_f32 v[190:191], v[82:83], v[174:175]
	v_add_f32_e32 v196, v190, v191
	v_pk_mul_f32 v[192:193], v[82:83], v[204:205]
	v_pk_mul_f32 v[194:195], v[82:83], v[176:177]
	v_add_f32_dpp v196, v196, v196 quad_perm:[1,0,3,2] row_mask:0xf bank_mask:0xf bound_ctrl:1
	v_add_f32_e32 v198, v192, v193
	v_pk_fma_f32 v[194:195], v[202:203], v[178:179], v[194:195] op_sel:[1,0,0] op_sel_hi:[1,1,1]
	v_add_f32_dpp v196, v196, v196 quad_perm:[2,3,0,1] row_mask:0xf bank_mask:0xf bound_ctrl:1
	v_add_f32_dpp v198, v198, v198 quad_perm:[1,0,3,2] row_mask:0xf bank_mask:0xf bound_ctrl:1
	s_nop 0
	v_add_f32_dpp v196, v196, v196 row_half_mirror row_mask:0xf bank_mask:0xf bound_ctrl:1
	s_nop 1
	v_add_f32_dpp v196, v196, v196 row_mirror row_mask:0xf bank_mask:0xf bound_ctrl:1
	v_mov_b32_e32 v197, v196
	s_nop 1
	v_permlane16_swap_b32_e32 v196, v197
	v_add_f32_e32 v196, v196, v197
	v_pk_fma_f32 v[82:83], v[196:197], v[180:181], v[194:195] op_sel_hi:[0,1,1] neg_lo:[1,0,0] neg_hi:[1,0,0]
	ds_read2st64_b64 v[174:177], v153 offset0:54 offset1:38
	ds_read2st64_b64 v[178:181], v153 offset0:22 offset1:70
	ds_read2_b64 v[186:189], v160 offset0:128 offset1:160
	s_waitcnt lgkmcnt(3)
	v_pk_mul_f32 v[190:191], v[82:83], v[162:163]
	v_add_f32_e32 v196, v190, v191
	v_pk_mul_f32 v[192:193], v[82:83], v[206:207]
	v_pk_mul_f32 v[194:195], v[82:83], v[164:165]
	v_add_f32_dpp v196, v196, v196 quad_perm:[1,0,3,2] row_mask:0xf bank_mask:0xf bound_ctrl:1
	v_add_f32_e32 v199, v192, v193
	v_pk_fma_f32 v[194:195], v[200:201], v[166:167], v[194:195] op_sel_hi:[0,1,1]
	v_add_f32_dpp v196, v196, v196 quad_perm:[2,3,0,1] row_mask:0xf bank_mask:0xf bound_ctrl:1
	v_add_f32_dpp v199, v199, v199 quad_perm:[1,0,3,2] row_mask:0xf bank_mask:0xf bound_ctrl:1
	ds_write2st64_b32 v100, v198, v199 offset0:20 offset1:22
	v_add_f32_dpp v196, v196, v196 row_half_mirror row_mask:0xf bank_mask:0xf bound_ctrl:1
	s_nop 1
	v_add_f32_dpp v196, v196, v196 row_mirror row_mask:0xf bank_mask:0xf bound_ctrl:1
	v_mov_b32_e32 v197, v196
	s_nop 1
	v_permlane16_swap_b32_e32 v196, v197
	v_add_f32_e32 v196, v196, v197
	v_pk_fma_f32 v[82:83], v[196:197], v[168:169], v[194:195] op_sel_hi:[0,1,1] neg_lo:[1,0,0] neg_hi:[1,0,0]
	ds_read2st64_b64 v[162:165], v98 offset0:55 offset1:39
	ds_read2st64_b64 v[166:169], v98 offset0:23 offset1:71
	ds_read2_b32 v[202:203], v99 offset0:224 offset1:240
	s_waitcnt lgkmcnt(4)
	v_pk_mul_f32 v[190:191], v[82:83], v[174:175]
	v_add_f32_e32 v196, v190, v191
	v_pk_mul_f32 v[192:193], v[82:83], v[186:187]
	v_pk_mul_f32 v[194:195], v[82:83], v[176:177]
	v_add_f32_dpp v196, v196, v196 quad_perm:[1,0,3,2] row_mask:0xf bank_mask:0xf bound_ctrl:1
	v_add_f32_e32 v198, v192, v193
	v_pk_fma_f32 v[194:195], v[200:201], v[178:179], v[194:195] op_sel:[1,0,0] op_sel_hi:[1,1,1]
	v_add_f32_dpp v196, v196, v196 quad_perm:[2,3,0,1] row_mask:0xf bank_mask:0xf bound_ctrl:1
	v_add_f32_dpp v198, v198, v198 quad_perm:[1,0,3,2] row_mask:0xf bank_mask:0xf bound_ctrl:1
	s_nop 0
	v_add_f32_dpp v196, v196, v196 row_half_mirror row_mask:0xf bank_mask:0xf bound_ctrl:1
	s_nop 1
	v_add_f32_dpp v196, v196, v196 row_mirror row_mask:0xf bank_mask:0xf bound_ctrl:1
	v_mov_b32_e32 v197, v196
	s_nop 1
	v_permlane16_swap_b32_e32 v196, v197
	v_add_f32_e32 v196, v196, v197
	v_pk_fma_f32 v[82:83], v[196:197], v[180:181], v[194:195] op_sel_hi:[0,1,1] neg_lo:[1,0,0] neg_hi:[1,0,0]
	ds_read2st64_b64 v[174:177], v153 offset0:55 offset1:39
	ds_read2st64_b64 v[178:181], v153 offset0:23 offset1:71
	ds_read2_b64 v[204:207], v160 offset0:192 offset1:224
	s_waitcnt lgkmcnt(3)
	v_pk_mul_f32 v[190:191], v[82:83], v[162:163]
	v_add_f32_e32 v196, v190, v191
	v_pk_mul_f32 v[192:193], v[82:83], v[188:189]
	v_pk_mul_f32 v[194:195], v[82:83], v[164:165]
	v_add_f32_dpp v196, v196, v196 quad_perm:[1,0,3,2] row_mask:0xf bank_mask:0xf bound_ctrl:1
	v_add_f32_e32 v199, v192, v193
	v_pk_fma_f32 v[194:195], v[202:203], v[166:167], v[194:195] op_sel_hi:[0,1,1]
	v_add_f32_dpp v196, v196, v196 quad_perm:[2,3,0,1] row_mask:0xf bank_mask:0xf bound_ctrl:1
	v_add_f32_dpp v199, v199, v199 quad_perm:[1,0,3,2] row_mask:0xf bank_mask:0xf bound_ctrl:1
	ds_write2st64_b32 v100, v198, v199 offset0:24 offset1:26
	v_add_f32_dpp v196, v196, v196 row_half_mirror row_mask:0xf bank_mask:0xf bound_ctrl:1
	s_nop 1
	v_add_f32_dpp v196, v196, v196 row_mirror row_mask:0xf bank_mask:0xf bound_ctrl:1
	v_mov_b32_e32 v197, v196
	s_nop 1
	v_permlane16_swap_b32_e32 v196, v197
	v_add_f32_e32 v196, v196, v197
	v_pk_fma_f32 v[82:83], v[196:197], v[168:169], v[194:195] op_sel_hi:[0,1,1] neg_lo:[1,0,0] neg_hi:[1,0,0]
	ds_read2st64_b64 v[162:165], v98 offset0:56 offset1:40
	ds_read2st64_b64 v[166:169], v98 offset0:24 offset1:72
	ds_read2_b32 v[200:201], v159 offset0:0 offset1:16
	s_waitcnt lgkmcnt(4)
	v_pk_mul_f32 v[190:191], v[82:83], v[174:175]
	v_add_f32_e32 v196, v190, v191
	v_pk_mul_f32 v[192:193], v[82:83], v[204:205]
	v_pk_mul_f32 v[194:195], v[82:83], v[176:177]
	v_add_f32_dpp v196, v196, v196 quad_perm:[1,0,3,2] row_mask:0xf bank_mask:0xf bound_ctrl:1
	v_add_f32_e32 v198, v192, v193
	v_pk_fma_f32 v[194:195], v[202:203], v[178:179], v[194:195] op_sel:[1,0,0] op_sel_hi:[1,1,1]
	v_add_f32_dpp v196, v196, v196 quad_perm:[2,3,0,1] row_mask:0xf bank_mask:0xf bound_ctrl:1
	v_add_f32_dpp v198, v198, v198 quad_perm:[1,0,3,2] row_mask:0xf bank_mask:0xf bound_ctrl:1
	s_nop 0
	v_add_f32_dpp v196, v196, v196 row_half_mirror row_mask:0xf bank_mask:0xf bound_ctrl:1
	s_nop 1
	v_add_f32_dpp v196, v196, v196 row_mirror row_mask:0xf bank_mask:0xf bound_ctrl:1
	v_mov_b32_e32 v197, v196
	s_nop 1
	v_permlane16_swap_b32_e32 v196, v197
	v_add_f32_e32 v196, v196, v197
	v_pk_fma_f32 v[82:83], v[196:197], v[180:181], v[194:195] op_sel_hi:[0,1,1] neg_lo:[1,0,0] neg_hi:[1,0,0]
	ds_read2st64_b64 v[174:177], v153 offset0:56 offset1:40
	ds_read2st64_b64 v[178:181], v153 offset0:24 offset1:72
	ds_read2_b64 v[186:189], v230 offset0:0 offset1:32
	s_waitcnt lgkmcnt(3)
	v_pk_mul_f32 v[190:191], v[82:83], v[162:163]
	v_add_f32_e32 v196, v190, v191
	v_pk_mul_f32 v[192:193], v[82:83], v[206:207]
	v_pk_mul_f32 v[194:195], v[82:83], v[164:165]
	v_add_f32_dpp v196, v196, v196 quad_perm:[1,0,3,2] row_mask:0xf bank_mask:0xf bound_ctrl:1
	v_add_f32_e32 v199, v192, v193
	v_pk_fma_f32 v[194:195], v[200:201], v[166:167], v[194:195] op_sel_hi:[0,1,1]
	v_add_f32_dpp v196, v196, v196 quad_perm:[2,3,0,1] row_mask:0xf bank_mask:0xf bound_ctrl:1
	v_add_f32_dpp v199, v199, v199 quad_perm:[1,0,3,2] row_mask:0xf bank_mask:0xf bound_ctrl:1
	ds_write2st64_b32 v100, v198, v199 offset0:28 offset1:30
	v_add_f32_dpp v196, v196, v196 row_half_mirror row_mask:0xf bank_mask:0xf bound_ctrl:1
	s_nop 1
	v_add_f32_dpp v196, v196, v196 row_mirror row_mask:0xf bank_mask:0xf bound_ctrl:1
	v_mov_b32_e32 v197, v196
	s_nop 1
	v_permlane16_swap_b32_e32 v196, v197
	v_add_f32_e32 v196, v196, v197
	v_pk_fma_f32 v[82:83], v[196:197], v[168:169], v[194:195] op_sel_hi:[0,1,1] neg_lo:[1,0,0] neg_hi:[1,0,0]
	ds_read2st64_b64 v[162:165], v98 offset0:57 offset1:41
	ds_read2st64_b64 v[166:169], v98 offset0:25 offset1:73
	ds_read2_b32 v[202:203], v159 offset0:32 offset1:48
	s_waitcnt lgkmcnt(4)
	v_pk_mul_f32 v[190:191], v[82:83], v[174:175]
	v_add_f32_e32 v196, v190, v191
	v_pk_mul_f32 v[192:193], v[82:83], v[186:187]
	v_pk_mul_f32 v[194:195], v[82:83], v[176:177]
	v_add_f32_dpp v196, v196, v196 quad_perm:[1,0,3,2] row_mask:0xf bank_mask:0xf bound_ctrl:1
	v_add_f32_e32 v198, v192, v193
	v_pk_fma_f32 v[194:195], v[200:201], v[178:179], v[194:195] op_sel:[1,0,0] op_sel_hi:[1,1,1]
	v_add_f32_dpp v196, v196, v196 quad_perm:[2,3,0,1] row_mask:0xf bank_mask:0xf bound_ctrl:1
	v_add_f32_dpp v198, v198, v198 quad_perm:[1,0,3,2] row_mask:0xf bank_mask:0xf bound_ctrl:1
	s_nop 0
	v_add_f32_dpp v196, v196, v196 row_half_mirror row_mask:0xf bank_mask:0xf bound_ctrl:1
	s_nop 1
	v_add_f32_dpp v196, v196, v196 row_mirror row_mask:0xf bank_mask:0xf bound_ctrl:1
	v_mov_b32_e32 v197, v196
	s_nop 1
	v_permlane16_swap_b32_e32 v196, v197
	v_add_f32_e32 v196, v196, v197
	v_pk_fma_f32 v[82:83], v[196:197], v[180:181], v[194:195] op_sel_hi:[0,1,1] neg_lo:[1,0,0] neg_hi:[1,0,0]
	ds_read2st64_b64 v[174:177], v153 offset0:57 offset1:41
	ds_read2st64_b64 v[178:181], v153 offset0:25 offset1:73
	ds_read2_b64 v[204:207], v230 offset0:64 offset1:96
	s_waitcnt lgkmcnt(3)
	v_pk_mul_f32 v[190:191], v[82:83], v[162:163]
	v_add_f32_e32 v196, v190, v191
	v_pk_mul_f32 v[192:193], v[82:83], v[188:189]
	v_pk_mul_f32 v[194:195], v[82:83], v[164:165]
	v_add_f32_dpp v196, v196, v196 quad_perm:[1,0,3,2] row_mask:0xf bank_mask:0xf bound_ctrl:1
	v_add_f32_e32 v199, v192, v193
	v_pk_fma_f32 v[194:195], v[202:203], v[166:167], v[194:195] op_sel_hi:[0,1,1]
	v_add_f32_dpp v196, v196, v196 quad_perm:[2,3,0,1] row_mask:0xf bank_mask:0xf bound_ctrl:1
	v_add_f32_dpp v199, v199, v199 quad_perm:[1,0,3,2] row_mask:0xf bank_mask:0xf bound_ctrl:1
	ds_write2st64_b32 v100, v198, v199 offset0:32 offset1:34
	v_add_f32_dpp v196, v196, v196 row_half_mirror row_mask:0xf bank_mask:0xf bound_ctrl:1
	s_nop 1
	v_add_f32_dpp v196, v196, v196 row_mirror row_mask:0xf bank_mask:0xf bound_ctrl:1
	v_mov_b32_e32 v197, v196
	s_nop 1
	v_permlane16_swap_b32_e32 v196, v197
	v_add_f32_e32 v196, v196, v197
	v_pk_fma_f32 v[82:83], v[196:197], v[168:169], v[194:195] op_sel_hi:[0,1,1] neg_lo:[1,0,0] neg_hi:[1,0,0]
	ds_read2st64_b64 v[162:165], v98 offset0:58 offset1:42
	ds_read2st64_b64 v[166:169], v98 offset0:26 offset1:74
	ds_read2_b32 v[200:201], v159 offset0:64 offset1:80
	s_waitcnt lgkmcnt(4)
	v_pk_mul_f32 v[190:191], v[82:83], v[174:175]
	v_add_f32_e32 v196, v190, v191
	v_pk_mul_f32 v[192:193], v[82:83], v[204:205]
	v_pk_mul_f32 v[194:195], v[82:83], v[176:177]
	v_add_f32_dpp v196, v196, v196 quad_perm:[1,0,3,2] row_mask:0xf bank_mask:0xf bound_ctrl:1
	v_add_f32_e32 v198, v192, v193
	v_pk_fma_f32 v[194:195], v[202:203], v[178:179], v[194:195] op_sel:[1,0,0] op_sel_hi:[1,1,1]
	v_add_f32_dpp v196, v196, v196 quad_perm:[2,3,0,1] row_mask:0xf bank_mask:0xf bound_ctrl:1
	v_add_f32_dpp v198, v198, v198 quad_perm:[1,0,3,2] row_mask:0xf bank_mask:0xf bound_ctrl:1
	s_nop 0
	v_add_f32_dpp v196, v196, v196 row_half_mirror row_mask:0xf bank_mask:0xf bound_ctrl:1
	s_nop 1
	v_add_f32_dpp v196, v196, v196 row_mirror row_mask:0xf bank_mask:0xf bound_ctrl:1
	v_mov_b32_e32 v197, v196
	s_nop 1
	v_permlane16_swap_b32_e32 v196, v197
	v_add_f32_e32 v196, v196, v197
	v_pk_fma_f32 v[82:83], v[196:197], v[180:181], v[194:195] op_sel_hi:[0,1,1] neg_lo:[1,0,0] neg_hi:[1,0,0]
	ds_read2st64_b64 v[174:177], v153 offset0:58 offset1:42
	ds_read2st64_b64 v[178:181], v153 offset0:26 offset1:74
	ds_read2_b64 v[186:189], v230 offset0:128 offset1:160
	s_waitcnt lgkmcnt(3)
	v_pk_mul_f32 v[190:191], v[82:83], v[162:163]
	v_add_f32_e32 v196, v190, v191
	v_pk_mul_f32 v[192:193], v[82:83], v[206:207]
	v_pk_mul_f32 v[194:195], v[82:83], v[164:165]
	v_add_f32_dpp v196, v196, v196 quad_perm:[1,0,3,2] row_mask:0xf bank_mask:0xf bound_ctrl:1
	v_add_f32_e32 v199, v192, v193
	v_pk_fma_f32 v[194:195], v[200:201], v[166:167], v[194:195] op_sel_hi:[0,1,1]
	v_add_f32_dpp v196, v196, v196 quad_perm:[2,3,0,1] row_mask:0xf bank_mask:0xf bound_ctrl:1
	v_add_f32_dpp v199, v199, v199 quad_perm:[1,0,3,2] row_mask:0xf bank_mask:0xf bound_ctrl:1
	ds_write2st64_b32 v100, v198, v199 offset0:36 offset1:38
	v_add_f32_dpp v196, v196, v196 row_half_mirror row_mask:0xf bank_mask:0xf bound_ctrl:1
	s_nop 1
	v_add_f32_dpp v196, v196, v196 row_mirror row_mask:0xf bank_mask:0xf bound_ctrl:1
	v_mov_b32_e32 v197, v196
	s_nop 1
	v_permlane16_swap_b32_e32 v196, v197
	v_add_f32_e32 v196, v196, v197
	v_pk_fma_f32 v[82:83], v[196:197], v[168:169], v[194:195] op_sel_hi:[0,1,1] neg_lo:[1,0,0] neg_hi:[1,0,0]
	ds_read2st64_b64 v[162:165], v98 offset0:59 offset1:43
	ds_read2st64_b64 v[166:169], v98 offset0:27 offset1:75
	ds_read2_b32 v[202:203], v159 offset0:96 offset1:112
	s_waitcnt lgkmcnt(4)
	v_pk_mul_f32 v[190:191], v[82:83], v[174:175]
	v_add_f32_e32 v196, v190, v191
	v_pk_mul_f32 v[192:193], v[82:83], v[186:187]
	v_pk_mul_f32 v[194:195], v[82:83], v[176:177]
	v_add_f32_dpp v196, v196, v196 quad_perm:[1,0,3,2] row_mask:0xf bank_mask:0xf bound_ctrl:1
	v_add_f32_e32 v198, v192, v193
	v_pk_fma_f32 v[194:195], v[200:201], v[178:179], v[194:195] op_sel:[1,0,0] op_sel_hi:[1,1,1]
	v_add_f32_dpp v196, v196, v196 quad_perm:[2,3,0,1] row_mask:0xf bank_mask:0xf bound_ctrl:1
	v_add_f32_dpp v198, v198, v198 quad_perm:[1,0,3,2] row_mask:0xf bank_mask:0xf bound_ctrl:1
	s_nop 0
	v_add_f32_dpp v196, v196, v196 row_half_mirror row_mask:0xf bank_mask:0xf bound_ctrl:1
	s_nop 1
	v_add_f32_dpp v196, v196, v196 row_mirror row_mask:0xf bank_mask:0xf bound_ctrl:1
	v_mov_b32_e32 v197, v196
	s_nop 1
	v_permlane16_swap_b32_e32 v196, v197
	v_add_f32_e32 v196, v196, v197
	v_pk_fma_f32 v[82:83], v[196:197], v[180:181], v[194:195] op_sel_hi:[0,1,1] neg_lo:[1,0,0] neg_hi:[1,0,0]
	ds_read2st64_b64 v[174:177], v153 offset0:59 offset1:43
	ds_read2st64_b64 v[178:181], v153 offset0:27 offset1:75
	ds_read2_b64 v[204:207], v230 offset0:192 offset1:224
	s_waitcnt lgkmcnt(3)
	v_pk_mul_f32 v[190:191], v[82:83], v[162:163]
	v_add_f32_e32 v196, v190, v191
	v_pk_mul_f32 v[192:193], v[82:83], v[188:189]
	v_pk_mul_f32 v[194:195], v[82:83], v[164:165]
	v_add_f32_dpp v196, v196, v196 quad_perm:[1,0,3,2] row_mask:0xf bank_mask:0xf bound_ctrl:1
	v_add_f32_e32 v199, v192, v193
	v_pk_fma_f32 v[194:195], v[202:203], v[166:167], v[194:195] op_sel_hi:[0,1,1]
	v_add_f32_dpp v196, v196, v196 quad_perm:[2,3,0,1] row_mask:0xf bank_mask:0xf bound_ctrl:1
	v_add_f32_dpp v199, v199, v199 quad_perm:[1,0,3,2] row_mask:0xf bank_mask:0xf bound_ctrl:1
	ds_write2st64_b32 v100, v198, v199 offset0:40 offset1:42
	v_add_f32_dpp v196, v196, v196 row_half_mirror row_mask:0xf bank_mask:0xf bound_ctrl:1
	s_nop 1
	v_add_f32_dpp v196, v196, v196 row_mirror row_mask:0xf bank_mask:0xf bound_ctrl:1
	v_mov_b32_e32 v197, v196
	s_nop 1
	v_permlane16_swap_b32_e32 v196, v197
	v_add_f32_e32 v196, v196, v197
	v_pk_fma_f32 v[82:83], v[196:197], v[168:169], v[194:195] op_sel_hi:[0,1,1] neg_lo:[1,0,0] neg_hi:[1,0,0]
	ds_read2st64_b64 v[162:165], v98 offset0:60 offset1:44
	ds_read2st64_b64 v[166:169], v98 offset0:28 offset1:76
	ds_read2_b32 v[200:201], v159 offset0:128 offset1:144
	s_waitcnt lgkmcnt(4)
	v_pk_mul_f32 v[190:191], v[82:83], v[174:175]
	v_add_f32_e32 v196, v190, v191
	v_pk_mul_f32 v[192:193], v[82:83], v[204:205]
	v_pk_mul_f32 v[194:195], v[82:83], v[176:177]
	v_add_f32_dpp v196, v196, v196 quad_perm:[1,0,3,2] row_mask:0xf bank_mask:0xf bound_ctrl:1
	v_add_f32_e32 v198, v192, v193
	v_pk_fma_f32 v[194:195], v[202:203], v[178:179], v[194:195] op_sel:[1,0,0] op_sel_hi:[1,1,1]
	v_add_f32_dpp v196, v196, v196 quad_perm:[2,3,0,1] row_mask:0xf bank_mask:0xf bound_ctrl:1
	v_add_f32_dpp v198, v198, v198 quad_perm:[1,0,3,2] row_mask:0xf bank_mask:0xf bound_ctrl:1
	s_nop 0
	v_add_f32_dpp v196, v196, v196 row_half_mirror row_mask:0xf bank_mask:0xf bound_ctrl:1
	s_nop 1
	v_add_f32_dpp v196, v196, v196 row_mirror row_mask:0xf bank_mask:0xf bound_ctrl:1
	v_mov_b32_e32 v197, v196
	s_nop 1
	v_permlane16_swap_b32_e32 v196, v197
	v_add_f32_e32 v196, v196, v197
	v_pk_fma_f32 v[82:83], v[196:197], v[180:181], v[194:195] op_sel_hi:[0,1,1] neg_lo:[1,0,0] neg_hi:[1,0,0]
	ds_read2st64_b64 v[174:177], v153 offset0:60 offset1:44
	ds_read2st64_b64 v[178:181], v153 offset0:28 offset1:76
	ds_read2_b64 v[186:189], v231 offset0:0 offset1:32
	s_waitcnt lgkmcnt(3)
	v_pk_mul_f32 v[190:191], v[82:83], v[162:163]
	v_add_f32_e32 v196, v190, v191
	v_pk_mul_f32 v[192:193], v[82:83], v[206:207]
	v_pk_mul_f32 v[194:195], v[82:83], v[164:165]
	v_add_f32_dpp v196, v196, v196 quad_perm:[1,0,3,2] row_mask:0xf bank_mask:0xf bound_ctrl:1
	v_add_f32_e32 v199, v192, v193
	v_pk_fma_f32 v[194:195], v[200:201], v[166:167], v[194:195] op_sel_hi:[0,1,1]
	v_add_f32_dpp v196, v196, v196 quad_perm:[2,3,0,1] row_mask:0xf bank_mask:0xf bound_ctrl:1
	v_add_f32_dpp v199, v199, v199 quad_perm:[1,0,3,2] row_mask:0xf bank_mask:0xf bound_ctrl:1
	ds_write2st64_b32 v100, v198, v199 offset0:44 offset1:46
	v_add_f32_dpp v196, v196, v196 row_half_mirror row_mask:0xf bank_mask:0xf bound_ctrl:1
	s_nop 1
	v_add_f32_dpp v196, v196, v196 row_mirror row_mask:0xf bank_mask:0xf bound_ctrl:1
	v_mov_b32_e32 v197, v196
	s_nop 1
	v_permlane16_swap_b32_e32 v196, v197
	v_add_f32_e32 v196, v196, v197
	v_pk_fma_f32 v[82:83], v[196:197], v[168:169], v[194:195] op_sel_hi:[0,1,1] neg_lo:[1,0,0] neg_hi:[1,0,0]
	ds_read2st64_b64 v[162:165], v98 offset0:61 offset1:45
	ds_read2st64_b64 v[166:169], v98 offset0:29 offset1:77
	ds_read2_b32 v[202:203], v159 offset0:160 offset1:176
	s_waitcnt lgkmcnt(4)
	v_pk_mul_f32 v[190:191], v[82:83], v[174:175]
	v_add_f32_e32 v196, v190, v191
	v_pk_mul_f32 v[192:193], v[82:83], v[186:187]
	v_pk_mul_f32 v[194:195], v[82:83], v[176:177]
	v_add_f32_dpp v196, v196, v196 quad_perm:[1,0,3,2] row_mask:0xf bank_mask:0xf bound_ctrl:1
	v_add_f32_e32 v198, v192, v193
	v_pk_fma_f32 v[194:195], v[200:201], v[178:179], v[194:195] op_sel:[1,0,0] op_sel_hi:[1,1,1]
	v_add_f32_dpp v196, v196, v196 quad_perm:[2,3,0,1] row_mask:0xf bank_mask:0xf bound_ctrl:1
	v_add_f32_dpp v198, v198, v198 quad_perm:[1,0,3,2] row_mask:0xf bank_mask:0xf bound_ctrl:1
	s_nop 0
	v_add_f32_dpp v196, v196, v196 row_half_mirror row_mask:0xf bank_mask:0xf bound_ctrl:1
	s_nop 1
	v_add_f32_dpp v196, v196, v196 row_mirror row_mask:0xf bank_mask:0xf bound_ctrl:1
	v_mov_b32_e32 v197, v196
	s_nop 1
	v_permlane16_swap_b32_e32 v196, v197
	v_add_f32_e32 v196, v196, v197
	v_pk_fma_f32 v[82:83], v[196:197], v[180:181], v[194:195] op_sel_hi:[0,1,1] neg_lo:[1,0,0] neg_hi:[1,0,0]
	ds_read2st64_b64 v[174:177], v153 offset0:61 offset1:45
	ds_read2st64_b64 v[178:181], v153 offset0:29 offset1:77
	ds_read2_b64 v[204:207], v231 offset0:64 offset1:96
	s_waitcnt lgkmcnt(3)
	v_pk_mul_f32 v[190:191], v[82:83], v[162:163]
	v_add_f32_e32 v196, v190, v191
	v_pk_mul_f32 v[192:193], v[82:83], v[188:189]
	v_pk_mul_f32 v[194:195], v[82:83], v[164:165]
	v_add_f32_dpp v196, v196, v196 quad_perm:[1,0,3,2] row_mask:0xf bank_mask:0xf bound_ctrl:1
	v_add_f32_e32 v199, v192, v193
	v_pk_fma_f32 v[194:195], v[202:203], v[166:167], v[194:195] op_sel_hi:[0,1,1]
	v_add_f32_dpp v196, v196, v196 quad_perm:[2,3,0,1] row_mask:0xf bank_mask:0xf bound_ctrl:1
	v_add_f32_dpp v199, v199, v199 quad_perm:[1,0,3,2] row_mask:0xf bank_mask:0xf bound_ctrl:1
	ds_write2st64_b32 v100, v198, v199 offset0:48 offset1:50
	v_add_f32_dpp v196, v196, v196 row_half_mirror row_mask:0xf bank_mask:0xf bound_ctrl:1
	s_nop 1
	v_add_f32_dpp v196, v196, v196 row_mirror row_mask:0xf bank_mask:0xf bound_ctrl:1
	v_mov_b32_e32 v197, v196
	s_nop 1
	v_permlane16_swap_b32_e32 v196, v197
	v_add_f32_e32 v196, v196, v197
	v_pk_fma_f32 v[82:83], v[196:197], v[168:169], v[194:195] op_sel_hi:[0,1,1] neg_lo:[1,0,0] neg_hi:[1,0,0]
	ds_read2st64_b64 v[162:165], v98 offset0:62 offset1:46
	ds_read2st64_b64 v[166:169], v98 offset0:30 offset1:78
	ds_read2_b32 v[200:201], v159 offset0:192 offset1:208
	s_waitcnt lgkmcnt(4)
	v_pk_mul_f32 v[190:191], v[82:83], v[174:175]
	v_add_f32_e32 v196, v190, v191
	v_pk_mul_f32 v[192:193], v[82:83], v[204:205]
	v_pk_mul_f32 v[194:195], v[82:83], v[176:177]
	v_add_f32_dpp v196, v196, v196 quad_perm:[1,0,3,2] row_mask:0xf bank_mask:0xf bound_ctrl:1
	v_add_f32_e32 v198, v192, v193
	v_pk_fma_f32 v[194:195], v[202:203], v[178:179], v[194:195] op_sel:[1,0,0] op_sel_hi:[1,1,1]
	v_add_f32_dpp v196, v196, v196 quad_perm:[2,3,0,1] row_mask:0xf bank_mask:0xf bound_ctrl:1
	v_add_f32_dpp v198, v198, v198 quad_perm:[1,0,3,2] row_mask:0xf bank_mask:0xf bound_ctrl:1
	s_nop 0
	v_add_f32_dpp v196, v196, v196 row_half_mirror row_mask:0xf bank_mask:0xf bound_ctrl:1
	s_nop 1
	v_add_f32_dpp v196, v196, v196 row_mirror row_mask:0xf bank_mask:0xf bound_ctrl:1
	v_mov_b32_e32 v197, v196
	s_nop 1
	v_permlane16_swap_b32_e32 v196, v197
	v_add_f32_e32 v196, v196, v197
	v_pk_fma_f32 v[82:83], v[196:197], v[180:181], v[194:195] op_sel_hi:[0,1,1] neg_lo:[1,0,0] neg_hi:[1,0,0]
	ds_read2st64_b64 v[174:177], v153 offset0:62 offset1:46
	ds_read2st64_b64 v[178:181], v153 offset0:30 offset1:78
	ds_read2_b64 v[186:189], v231 offset0:128 offset1:160
	s_waitcnt lgkmcnt(3)
	v_pk_mul_f32 v[190:191], v[82:83], v[162:163]
	v_add_f32_e32 v196, v190, v191
	v_pk_mul_f32 v[192:193], v[82:83], v[206:207]
	v_pk_mul_f32 v[194:195], v[82:83], v[164:165]
	v_add_f32_dpp v196, v196, v196 quad_perm:[1,0,3,2] row_mask:0xf bank_mask:0xf bound_ctrl:1
	v_add_f32_e32 v199, v192, v193
	v_pk_fma_f32 v[194:195], v[200:201], v[166:167], v[194:195] op_sel_hi:[0,1,1]
	v_add_f32_dpp v196, v196, v196 quad_perm:[2,3,0,1] row_mask:0xf bank_mask:0xf bound_ctrl:1
	v_add_f32_dpp v199, v199, v199 quad_perm:[1,0,3,2] row_mask:0xf bank_mask:0xf bound_ctrl:1
	ds_write2st64_b32 v100, v198, v199 offset0:52 offset1:54
	v_add_f32_dpp v196, v196, v196 row_half_mirror row_mask:0xf bank_mask:0xf bound_ctrl:1
	s_nop 1
	v_add_f32_dpp v196, v196, v196 row_mirror row_mask:0xf bank_mask:0xf bound_ctrl:1
	v_mov_b32_e32 v197, v196
	s_nop 1
	v_permlane16_swap_b32_e32 v196, v197
	v_add_f32_e32 v196, v196, v197
	v_pk_fma_f32 v[82:83], v[196:197], v[168:169], v[194:195] op_sel_hi:[0,1,1] neg_lo:[1,0,0] neg_hi:[1,0,0]
	ds_read2st64_b64 v[162:165], v98 offset0:63 offset1:47
	ds_read2st64_b64 v[166:169], v98 offset0:31 offset1:79
	ds_read2_b32 v[202:203], v159 offset0:224 offset1:240
	s_waitcnt lgkmcnt(4)
	v_pk_mul_f32 v[190:191], v[82:83], v[174:175]
	v_add_f32_e32 v196, v190, v191
	v_pk_mul_f32 v[192:193], v[82:83], v[186:187]
	v_pk_mul_f32 v[194:195], v[82:83], v[176:177]
	v_add_f32_dpp v196, v196, v196 quad_perm:[1,0,3,2] row_mask:0xf bank_mask:0xf bound_ctrl:1
	v_add_f32_e32 v198, v192, v193
	v_pk_fma_f32 v[194:195], v[200:201], v[178:179], v[194:195] op_sel:[1,0,0] op_sel_hi:[1,1,1]
	v_add_f32_dpp v196, v196, v196 quad_perm:[2,3,0,1] row_mask:0xf bank_mask:0xf bound_ctrl:1
	v_add_f32_dpp v198, v198, v198 quad_perm:[1,0,3,2] row_mask:0xf bank_mask:0xf bound_ctrl:1
	s_nop 0
	v_add_f32_dpp v196, v196, v196 row_half_mirror row_mask:0xf bank_mask:0xf bound_ctrl:1
	s_nop 1
	v_add_f32_dpp v196, v196, v196 row_mirror row_mask:0xf bank_mask:0xf bound_ctrl:1
	v_mov_b32_e32 v197, v196
	s_nop 1
	v_permlane16_swap_b32_e32 v196, v197
	v_add_f32_e32 v196, v196, v197
	v_pk_fma_f32 v[82:83], v[196:197], v[180:181], v[194:195] op_sel_hi:[0,1,1] neg_lo:[1,0,0] neg_hi:[1,0,0]
	ds_read2st64_b64 v[174:177], v153 offset0:63 offset1:47
	ds_read2st64_b64 v[178:181], v153 offset0:31 offset1:79
	ds_read2_b64 v[204:207], v231 offset0:192 offset1:224
	s_waitcnt lgkmcnt(3)
	v_pk_mul_f32 v[190:191], v[82:83], v[162:163]
	v_add_f32_e32 v196, v190, v191
	v_pk_mul_f32 v[192:193], v[82:83], v[188:189]
	v_pk_mul_f32 v[194:195], v[82:83], v[164:165]
	v_add_f32_dpp v196, v196, v196 quad_perm:[1,0,3,2] row_mask:0xf bank_mask:0xf bound_ctrl:1
	v_add_f32_e32 v199, v192, v193
	v_pk_fma_f32 v[194:195], v[202:203], v[166:167], v[194:195] op_sel_hi:[0,1,1]
	v_add_f32_dpp v196, v196, v196 quad_perm:[2,3,0,1] row_mask:0xf bank_mask:0xf bound_ctrl:1
	v_add_f32_dpp v199, v199, v199 quad_perm:[1,0,3,2] row_mask:0xf bank_mask:0xf bound_ctrl:1
	ds_write2st64_b32 v100, v198, v199 offset0:56 offset1:58
	v_add_f32_dpp v196, v196, v196 row_half_mirror row_mask:0xf bank_mask:0xf bound_ctrl:1
	s_nop 1
	v_add_f32_dpp v196, v196, v196 row_mirror row_mask:0xf bank_mask:0xf bound_ctrl:1
	v_mov_b32_e32 v197, v196
	s_nop 1
	v_permlane16_swap_b32_e32 v196, v197
	v_add_f32_e32 v196, v196, v197
	v_pk_fma_f32 v[82:83], v[196:197], v[168:169], v[194:195] op_sel_hi:[0,1,1] neg_lo:[1,0,0] neg_hi:[1,0,0]
	s_waitcnt lgkmcnt(1)
	v_pk_mul_f32 v[190:191], v[82:83], v[174:175]
	v_add_f32_e32 v196, v190, v191
	v_pk_mul_f32 v[192:193], v[82:83], v[204:205]
	v_pk_mul_f32 v[194:195], v[82:83], v[176:177]
	v_add_f32_dpp v196, v196, v196 quad_perm:[1,0,3,2] row_mask:0xf bank_mask:0xf bound_ctrl:1
	v_add_f32_e32 v198, v192, v193
	v_pk_fma_f32 v[194:195], v[202:203], v[178:179], v[194:195] op_sel:[1,0,0] op_sel_hi:[1,1,1]
	v_add_f32_dpp v196, v196, v196 quad_perm:[2,3,0,1] row_mask:0xf bank_mask:0xf bound_ctrl:1
	v_add_f32_dpp v198, v198, v198 quad_perm:[1,0,3,2] row_mask:0xf bank_mask:0xf bound_ctrl:1
	s_nop 0
	v_add_f32_dpp v196, v196, v196 row_half_mirror row_mask:0xf bank_mask:0xf bound_ctrl:1
	s_nop 1
	v_add_f32_dpp v196, v196, v196 row_mirror row_mask:0xf bank_mask:0xf bound_ctrl:1
	v_mov_b32_e32 v197, v196
	s_nop 1
	v_permlane16_swap_b32_e32 v196, v197
	v_add_f32_e32 v196, v196, v197
	v_pk_fma_f32 v[82:83], v[196:197], v[180:181], v[194:195] op_sel_hi:[0,1,1] neg_lo:[1,0,0] neg_hi:[1,0,0]
	v_pk_mul_f32 v[192:193], v[82:83], v[206:207]
	v_add_f32_e32 v199, v192, v193
	s_nop 1
	v_add_f32_dpp v199, v199, v199 quad_perm:[1,0,3,2] row_mask:0xf bank_mask:0xf bound_ctrl:1
	ds_write2st64_b32 v100, v198, v199 offset0:60 offset1:62
